# GEMM1 and gate/up GEMM epilogue stores plus their deferred weight-conversion stores made sc1 write-through so the seam flush finds little dirty L2 data
# speedup vs baseline: 1.0125x; 1.0002x over previous
; #define PG8_STAGE(bufoff, gbase, voff) do { _Pragma("unroll") for (int _i = 0; _i < 2; ++_i) \
;         __builtin_amdgcn_global_load_lds((const unsigned*)((const char*)(gbase) + (voff)[_i]), (LAS unsigned*)(lds + (bufoff) + ldsw + _i * 8192), 16, 0, 0); } while (0)
; #define PG8_LDA(dst, b, h) do { _Pragma("unroll") for (int m = 0; m < 4; ++m) _Pragma("unroll") for (int k = 0; k < 2; ++k) dst[m][k] = *(const LAS bf16x8*)(lds + PG8_SA(b, h) + aoff + m * 2048 + k * 1024); } while (0)
; #define PG8_LDB(dst, b, h) do { _Pragma("unroll") for (int n = 0; n < 2; ++n) _Pragma("unroll") for (int k = 0; k < 2; ++k) dst[n][k] = *(const LAS bf16x8*)(lds + PG8_SB(b, h) + boff + n * 2048 + k * 1024); } while (0)
; #define PG8_MMA(ai, bj, At, Bt) do { __builtin_amdgcn_s_setprio(1); _Pragma("unroll") for (int m = 0; m < 4; ++m) _Pragma("unroll") for (int n = 0; n < 2; ++n) _Pragma("unroll") for (int k = 0; k < 2; ++k) \
;         acc[ai][bj][m][n] = __builtin_amdgcn_mfma_f32_16x16x32_bf16(Bt[n][k], At[m][k], acc[ai][bj][m][n], 0, 0, 0); __builtin_amdgcn_s_setprio(0); } while (0)
; #define PG8_WAIT_L(n) asm volatile("s_waitcnt lgkmcnt(" #n ")" ::: "memory")
; #define PG8_BAR __builtin_amdgcn_s_barrier()
; #define PG8_SCHED __builtin_amdgcn_sched_barrier(0)
; template <class Epi>
; __device__ __forceinline__ void gemm_phase(LAS unsigned char* lds, const Gemm g, const StaticOrder& S, const Epi& E) {
;     ...
;             PG8_LDB(B0, 0, 0); PG8_SCHED; PG8_LDA(At, 0, 0); PG8_STAGE(PG8_SA(1, 1), a1 + hstep, voffA);
;             PG8_WAIT_L(8); PG8_BAR; PG8_WAIT_L(0); PG8_MMA(0, 0, At, B0); PG8_BAR; PG8_SCHED;
;             PG8_LDB(B1, 0, 1); PG8_STAGE(PG8_SB(0, 0), b2, voffB);
;             PG8_BAR; PG8_WAIT_L(0); PG8_MMA(0, 1, At, B1); PG8_BAR;
;             PG8_LDA(At, 0, 1); PG8_STAGE(PG8_SA(0, 0), a2, voffA);
;             PG8_BAR; PG8_WAIT_L(0); PG8_MMA(1, 0, At, B0); PG8_BAR; PG8_SCHED;
.LBB0_136:
	ds_read_b128 v[144:147], v154
	ds_read_b128 v[158:161], v154 offset:1024
	ds_read_b128 v[162:165], v154 offset:2048
	ds_read_b128 v[166:169], v154 offset:3072
	s_add_u32 s24, s22, 0xfff80080
	s_addc_u32 s25, s23, -1
	s_cmp_eq_u32 s77, 28
	s_cselect_b32 s27, s11, s25
	s_cselect_b32 s26, s73, s24
	s_cselect_b32 s25, s9, s76
	s_cselect_b32 s24, s74, s75
	v_lshl_add_u64 v[202:203], s[22:23], 0, v[136:137]
	s_add_i32 m0, s17, 0xc000
	ds_read_b128 v[170:173], v155
	ds_read_b128 v[174:177], v155 offset:1024
	ds_read_b128 v[178:181], v155 offset:2048
	ds_read_b128 v[182:185], v155 offset:3072
	ds_read_b128 v[186:189], v155 offset:4096
	ds_read_b128 v[190:193], v155 offset:5120
	ds_read_b128 v[194:197], v155 offset:6144
	ds_read_b128 v[198:201], v155 offset:7168
	global_load_lds_dwordx4 v[202:203], off
	v_lshl_add_u64 v[202:203], s[22:23], 0, v[138:139]
	s_add_i32 m0, s17, 0xe000
	s_nop 0
	global_load_lds_dwordx4 v[202:203], off
	s_waitcnt lgkmcnt(8)
	s_barrier
	s_waitcnt lgkmcnt(0)
	s_waitcnt lgkmcnt(0)
	v_mfma_f32_16x16x32_bf16 v[124:127], v[144:147], v[170:173], v[124:127]
	v_mfma_f32_16x16x32_bf16 v[120:123], v[162:165], v[170:173], v[120:123]
	v_mfma_f32_16x16x32_bf16 v[116:119], v[144:147], v[178:181], v[116:119]
	v_mfma_f32_16x16x32_bf16 v[108:111], v[162:165], v[178:181], v[108:111]
	v_mfma_f32_16x16x32_bf16 v[100:103], v[144:147], v[186:189], v[100:103]
	v_mfma_f32_16x16x32_bf16 v[92:95], v[162:165], v[186:189], v[92:95]
	v_mfma_f32_16x16x32_bf16 v[84:87], v[144:147], v[194:197], v[84:87]
	v_mfma_f32_16x16x32_bf16 v[76:79], v[162:165], v[194:197], v[76:79]
	v_mfma_f32_16x16x32_bf16 v[124:127], v[158:161], v[174:177], v[124:127]
	v_mfma_f32_16x16x32_bf16 v[120:123], v[166:169], v[174:177], v[120:123]
	v_mfma_f32_16x16x32_bf16 v[116:119], v[158:161], v[182:185], v[116:119]
	v_mfma_f32_16x16x32_bf16 v[108:111], v[166:169], v[182:185], v[108:111]
	v_mfma_f32_16x16x32_bf16 v[100:103], v[158:161], v[190:193], v[100:103]
	v_mfma_f32_16x16x32_bf16 v[92:95], v[166:169], v[190:193], v[92:95]
	v_mfma_f32_16x16x32_bf16 v[84:87], v[158:161], v[198:201], v[84:87]
	v_mfma_f32_16x16x32_bf16 v[76:79], v[166:169], v[198:201], v[76:79]
	s_barrier
	s_add_i32 s78, s69, s29
	v_lshl_add_u64 v[220:221], s[24:25], 0, v[130:131]
	s_mov_b32 m0, s78
	ds_read_b128 v[202:205], v156
	ds_read_b128 v[206:209], v156 offset:1024
	ds_read_b128 v[210:213], v156 offset:2048
	ds_read_b128 v[216:219], v156 offset:3072
	global_load_lds_dwordx4 v[220:221], off
	v_lshl_add_u64 v[222:223], s[24:25], 0, v[134:135]
	s_add_i32 m0, s78, 0x2000
	s_nop 0
	global_load_lds_dwordx4 v[222:223], off
	s_barrier
	s_waitcnt lgkmcnt(0)
	s_waitcnt lgkmcnt(0)
	v_mfma_f32_16x16x32_bf16 v[112:115], v[202:205], v[170:173], v[112:115]
	v_mfma_f32_16x16x32_bf16 v[104:107], v[210:213], v[170:173], v[104:107]
	v_mfma_f32_16x16x32_bf16 v[96:99], v[202:205], v[178:181], v[96:99]
	v_mfma_f32_16x16x32_bf16 v[88:91], v[210:213], v[178:181], v[88:91]
	v_mfma_f32_16x16x32_bf16 v[80:83], v[202:205], v[186:189], v[80:83]
	v_mfma_f32_16x16x32_bf16 v[72:75], v[210:213], v[186:189], v[72:75]
	v_mfma_f32_16x16x32_bf16 v[68:71], v[202:205], v[194:197], v[68:71]
	v_mfma_f32_16x16x32_bf16 v[64:67], v[210:213], v[194:197], v[64:67]
	v_mfma_f32_16x16x32_bf16 v[112:115], v[206:209], v[174:177], v[112:115]
	v_mfma_f32_16x16x32_bf16 v[104:107], v[216:219], v[174:177], v[104:107]
	v_mfma_f32_16x16x32_bf16 v[96:99], v[206:209], v[182:185], v[96:99]
	v_mfma_f32_16x16x32_bf16 v[88:91], v[216:219], v[182:185], v[88:91]
	v_mfma_f32_16x16x32_bf16 v[80:83], v[206:209], v[190:193], v[80:83]
	v_mfma_f32_16x16x32_bf16 v[72:75], v[216:219], v[190:193], v[72:75]
	v_mfma_f32_16x16x32_bf16 v[68:71], v[206:209], v[198:201], v[68:71]
	v_mfma_f32_16x16x32_bf16 v[64:67], v[216:219], v[198:201], v[64:67]
	s_mov_b32 m0, s17
	v_lshl_add_u64 v[224:225], s[26:27], 0, v[128:129]
	s_barrier
	ds_read_b128 v[170:173], v155 offset:16384
	ds_read_b128 v[174:177], v155 offset:17408
	ds_read_b128 v[178:181], v155 offset:18432
	ds_read_b128 v[182:185], v155 offset:19456
	ds_read_b128 v[186:189], v155 offset:20480
	ds_read_b128 v[190:193], v155 offset:21504
	ds_read_b128 v[194:197], v155 offset:22528
	ds_read_b128 v[198:201], v155 offset:23552
	global_load_lds_dwordx4 v[224:225], off
	v_lshl_add_u64 v[226:227], s[26:27], 0, v[132:133]
	s_mov_b32 m0, s30
	s_nop 0
	global_load_lds_dwordx4 v[226:227], off
	s_barrier
	s_waitcnt lgkmcnt(0)
	s_waitcnt lgkmcnt(0)
	v_mfma_f32_16x16x32_bf16 v[60:63], v[144:147], v[170:173], v[60:63]
	v_mfma_f32_16x16x32_bf16 v[56:59], v[162:165], v[170:173], v[56:59]
	v_mfma_f32_16x16x32_bf16 v[52:55], v[144:147], v[178:181], v[52:55]
	v_mfma_f32_16x16x32_bf16 v[44:47], v[162:165], v[178:181], v[44:47]
	v_mfma_f32_16x16x32_bf16 v[36:39], v[144:147], v[186:189], v[36:39]
	v_mfma_f32_16x16x32_bf16 v[28:31], v[162:165], v[186:189], v[28:31]
	v_mfma_f32_16x16x32_bf16 v[20:23], v[144:147], v[194:197], v[20:23]
	v_mfma_f32_16x16x32_bf16 v[12:15], v[162:165], v[194:197], v[12:15]
	v_mfma_f32_16x16x32_bf16 v[60:63], v[158:161], v[174:177], v[60:63]
	v_mfma_f32_16x16x32_bf16 v[56:59], v[166:169], v[174:177], v[56:59]
	v_mfma_f32_16x16x32_bf16 v[52:55], v[158:161], v[182:185], v[52:55]
	v_mfma_f32_16x16x32_bf16 v[44:47], v[166:169], v[182:185], v[44:47]
	v_mfma_f32_16x16x32_bf16 v[36:39], v[158:161], v[190:193], v[36:39]
	v_mfma_f32_16x16x32_bf16 v[28:31], v[166:169], v[190:193], v[28:31]
	v_mfma_f32_16x16x32_bf16 v[20:23], v[158:161], v[198:201], v[20:23]
	v_mfma_f32_16x16x32_bf16 v[12:15], v[166:169], v[198:201], v[12:15]
	s_barrier
; #define PG8_STAGE(bufoff, gbase, voff) do { _Pragma("unroll") for (int _i = 0; _i < 2; ++_i) \
;         __builtin_amdgcn_global_load_lds((const unsigned*)((const char*)(gbase) + (voff)[_i]), (LAS unsigned*)(lds + (bufoff) + ldsw + _i * 8192), 16, 0, 0); } while (0)
; #define PG8_LDA(dst, b, h) do { _Pragma("unroll") for (int m = 0; m < 4; ++m) _Pragma("unroll") for (int k = 0; k < 2; ++k) dst[m][k] = *(const LAS bf16x8*)(lds + PG8_SA(b, h) + aoff + m * 2048 + k * 1024); } while (0)
; #define PG8_LDB(dst, b, h) do { _Pragma("unroll") for (int n = 0; n < 2; ++n) _Pragma("unroll") for (int k = 0; k < 2; ++k) dst[n][k] = *(const LAS bf16x8*)(lds + PG8_SB(b, h) + boff + n * 2048 + k * 1024); } while (0)
; #define PG8_MMA(ai, bj, At, Bt) do { __builtin_amdgcn_s_setprio(1); _Pragma("unroll") for (int m = 0; m < 4; ++m) _Pragma("unroll") for (int n = 0; n < 2; ++n) _Pragma("unroll") for (int k = 0; k < 2; ++k) \
;         acc[ai][bj][m][n] = __builtin_amdgcn_mfma_f32_16x16x32_bf16(Bt[n][k], At[m][k], acc[ai][bj][m][n], 0, 0, 0); __builtin_amdgcn_s_setprio(0); } while (0)
; #define PG8_WAIT_V(n) asm volatile("s_waitcnt vmcnt(" #n ")" ::: "memory")
; #define PG8_WAIT_L(n) asm volatile("s_waitcnt lgkmcnt(" #n ")" ::: "memory")
; #define PG8_BAR __builtin_amdgcn_s_barrier()
; #define PG8_SCHED __builtin_amdgcn_sched_barrier(0)
; template <class Epi>
; __device__ __forceinline__ void gemm_phase(LAS unsigned char* lds, const Gemm g, const StaticOrder& S, const Epi& E) {
;     ...
;             PG8_BAR; PG8_WAIT_L(0); PG8_MMA(1, 0, At, B0); PG8_BAR; PG8_SCHED;
;             PG8_STAGE(PG8_SB(0, 1), b2 + hstep, voffB);
;             PG8_WAIT_V(6); PG8_BAR; PG8_MMA(1, 1, At, B1); PG8_BAR;
;             PG8_LDB(B0, 1, 0); PG8_SCHED; PG8_LDA(At, 1, 0); PG8_STAGE(PG8_SA(0, 1), a2 + hstep, voffA);
;             PG8_WAIT_L(8); PG8_BAR; PG8_WAIT_L(0); PG8_MMA(0, 0, At, B0); PG8_BAR; PG8_SCHED;
;             PG8_LDB(B1, 1, 1); PG8_STAGE(PG8_SB(1, 0), b3, voffB);
;             PG8_BAR; PG8_WAIT_L(0); PG8_MMA(0, 1, At, B1); PG8_BAR;
;             PG8_LDA(At, 1, 1); PG8_STAGE(PG8_SA(1, 0), a3, voffA);
	s_add_u32 s78, s24, 0x80000
	s_addc_u32 s79, s25, 0
	s_add_i32 s80, s70, s29
	v_lshl_add_u64 v[144:145], s[78:79], 0, v[130:131]
	s_mov_b32 m0, s80
	s_nop 0
	global_load_lds_dwordx4 v[144:145], off
	v_lshl_add_u64 v[144:145], s[78:79], 0, v[134:135]
	s_add_i32 m0, s80, 0x2000
	s_nop 0
	global_load_lds_dwordx4 v[144:145], off
	s_waitcnt vmcnt(6)
	s_barrier
	v_mfma_f32_16x16x32_bf16 v[48:51], v[202:205], v[170:173], v[48:51]
	v_mfma_f32_16x16x32_bf16 v[40:43], v[210:213], v[170:173], v[40:43]
	v_mfma_f32_16x16x32_bf16 v[32:35], v[202:205], v[178:181], v[32:35]
	v_mfma_f32_16x16x32_bf16 v[24:27], v[210:213], v[178:181], v[24:27]
	v_mfma_f32_16x16x32_bf16 v[16:19], v[202:205], v[186:189], v[16:19]
	v_mfma_f32_16x16x32_bf16 v[8:11], v[210:213], v[186:189], v[8:11]
	v_mfma_f32_16x16x32_bf16 v[4:7], v[202:205], v[194:197], v[4:7]
	v_mfma_f32_16x16x32_bf16 v[0:3], v[210:213], v[194:197], v[0:3]
	v_mfma_f32_16x16x32_bf16 v[48:51], v[206:209], v[174:177], v[48:51]
	v_mfma_f32_16x16x32_bf16 v[40:43], v[216:219], v[174:177], v[40:43]
	v_mfma_f32_16x16x32_bf16 v[32:35], v[206:209], v[182:185], v[32:35]
	v_mfma_f32_16x16x32_bf16 v[24:27], v[216:219], v[182:185], v[24:27]
	v_mfma_f32_16x16x32_bf16 v[16:19], v[206:209], v[190:193], v[16:19]
	v_mfma_f32_16x16x32_bf16 v[8:11], v[216:219], v[190:193], v[8:11]
	v_mfma_f32_16x16x32_bf16 v[4:7], v[206:209], v[198:201], v[4:7]
	v_mfma_f32_16x16x32_bf16 v[0:3], v[216:219], v[198:201], v[0:3]
	s_add_i32 s78, 0, 0x18000
	v_add_u32_e32 v157, s78, v152
	s_barrier
	ds_read_b128 v[144:147], v157
	ds_read_b128 v[158:161], v157 offset:1024
	ds_read_b128 v[162:165], v157 offset:2048
	ds_read_b128 v[166:169], v157 offset:3072
	s_add_u32 s26, s26, 0x80000
	s_addc_u32 s27, s27, 0
	s_mov_b32 m0, s31
	v_lshl_add_u64 v[202:203], s[26:27], 0, v[128:129]
	ds_read_b128 v[170:173], v155 offset:32768
	ds_read_b128 v[174:177], v155 offset:33792
	ds_read_b128 v[178:181], v155 offset:34816
	ds_read_b128 v[182:185], v155 offset:35840
	ds_read_b128 v[186:189], v155 offset:36864
	ds_read_b128 v[190:193], v155 offset:37888
	ds_read_b128 v[194:197], v155 offset:38912
	ds_read_b128 v[198:201], v155 offset:39936
	global_load_lds_dwordx4 v[202:203], off
	v_lshl_add_u64 v[202:203], s[26:27], 0, v[132:133]
	s_mov_b32 m0, s33
	s_nop 0
	global_load_lds_dwordx4 v[202:203], off
	s_waitcnt lgkmcnt(8)
	s_barrier
	s_waitcnt lgkmcnt(0)
	s_waitcnt lgkmcnt(0)
	v_mfma_f32_16x16x32_bf16 v[124:127], v[144:147], v[170:173], v[124:127]
	v_mfma_f32_16x16x32_bf16 v[120:123], v[162:165], v[170:173], v[120:123]
	v_mfma_f32_16x16x32_bf16 v[116:119], v[144:147], v[178:181], v[116:119]
	v_mfma_f32_16x16x32_bf16 v[108:111], v[162:165], v[178:181], v[108:111]
	v_mfma_f32_16x16x32_bf16 v[100:103], v[144:147], v[186:189], v[100:103]
	v_mfma_f32_16x16x32_bf16 v[92:95], v[162:165], v[186:189], v[92:95]
	v_mfma_f32_16x16x32_bf16 v[84:87], v[144:147], v[194:197], v[84:87]
	v_mfma_f32_16x16x32_bf16 v[76:79], v[162:165], v[194:197], v[76:79]
	v_mfma_f32_16x16x32_bf16 v[124:127], v[158:161], v[174:177], v[124:127]
	v_mfma_f32_16x16x32_bf16 v[120:123], v[166:169], v[174:177], v[120:123]
	v_mfma_f32_16x16x32_bf16 v[116:119], v[158:161], v[182:185], v[116:119]
	v_mfma_f32_16x16x32_bf16 v[108:111], v[166:169], v[182:185], v[108:111]
	v_mfma_f32_16x16x32_bf16 v[100:103], v[158:161], v[190:193], v[100:103]
	v_mfma_f32_16x16x32_bf16 v[92:95], v[166:169], v[190:193], v[92:95]
	v_mfma_f32_16x16x32_bf16 v[84:87], v[158:161], v[198:201], v[84:87]
	v_mfma_f32_16x16x32_bf16 v[76:79], v[166:169], v[198:201], v[76:79]
	s_barrier
	s_add_i32 s26, 0, 0x1c000
	s_add_i32 s27, s78, s29
	v_add_u32_e32 v157, s26, v152
	v_lshl_add_u64 v[220:221], v[220:221], 0, s[4:5]
	s_mov_b32 m0, s27
	ds_read_b128 v[202:205], v157
	ds_read_b128 v[206:209], v157 offset:1024
	ds_read_b128 v[210:213], v157 offset:2048
	ds_read_b128 v[216:219], v157 offset:3072
	global_load_lds_dwordx4 v[220:221], off
	v_lshl_add_u64 v[220:221], v[222:223], 0, s[4:5]
	s_add_i32 m0, s27, 0x2000
	s_nop 0
	global_load_lds_dwordx4 v[220:221], off
	s_barrier
	s_waitcnt lgkmcnt(0)
	s_waitcnt lgkmcnt(0)
	v_mfma_f32_16x16x32_bf16 v[112:115], v[202:205], v[170:173], v[112:115]
	v_mfma_f32_16x16x32_bf16 v[104:107], v[210:213], v[170:173], v[104:107]
	v_mfma_f32_16x16x32_bf16 v[96:99], v[202:205], v[178:181], v[96:99]
	v_mfma_f32_16x16x32_bf16 v[88:91], v[210:213], v[178:181], v[88:91]
	v_mfma_f32_16x16x32_bf16 v[80:83], v[202:205], v[186:189], v[80:83]
	v_mfma_f32_16x16x32_bf16 v[72:75], v[210:213], v[186:189], v[72:75]
	v_mfma_f32_16x16x32_bf16 v[68:71], v[202:205], v[194:197], v[68:71]
	v_mfma_f32_16x16x32_bf16 v[64:67], v[210:213], v[194:197], v[64:67]
	v_mfma_f32_16x16x32_bf16 v[112:115], v[206:209], v[174:177], v[112:115]
	v_mfma_f32_16x16x32_bf16 v[104:107], v[216:219], v[174:177], v[104:107]
	v_mfma_f32_16x16x32_bf16 v[96:99], v[206:209], v[182:185], v[96:99]
	v_mfma_f32_16x16x32_bf16 v[88:91], v[216:219], v[182:185], v[88:91]
	v_mfma_f32_16x16x32_bf16 v[80:83], v[206:209], v[190:193], v[80:83]
	v_mfma_f32_16x16x32_bf16 v[72:75], v[216:219], v[190:193], v[72:75]
	v_mfma_f32_16x16x32_bf16 v[68:71], v[206:209], v[198:201], v[68:71]
	v_mfma_f32_16x16x32_bf16 v[64:67], v[216:219], v[198:201], v[64:67]
	s_mov_b32 m0, s51
	v_lshl_add_u64 v[220:221], v[224:225], 0, s[4:5]
	s_barrier
	ds_read_b128 v[170:173], v155 offset:49152
	ds_read_b128 v[174:177], v155 offset:50176
	ds_read_b128 v[178:181], v155 offset:51200
	ds_read_b128 v[182:185], v155 offset:52224
	ds_read_b128 v[186:189], v155 offset:53248
	ds_read_b128 v[190:193], v155 offset:54272
	ds_read_b128 v[194:197], v155 offset:55296
	ds_read_b128 v[198:201], v155 offset:56320
	global_load_lds_dwordx4 v[220:221], off
	v_lshl_add_u64 v[220:221], v[226:227], 0, s[4:5]
	s_mov_b32 m0, s54
	s_nop 0
	global_load_lds_dwordx4 v[220:221], off
	s_barrier
; #define PG8_STAGE(bufoff, gbase, voff) do { _Pragma("unroll") for (int _i = 0; _i < 2; ++_i) \
;         __builtin_amdgcn_global_load_lds((const unsigned*)((const char*)(gbase) + (voff)[_i]), (LAS unsigned*)(lds + (bufoff) + ldsw + _i * 8192), 16, 0, 0); } while (0)
; #define PG8_LDA(dst, b, h) do { _Pragma("unroll") for (int m = 0; m < 4; ++m) _Pragma("unroll") for (int k = 0; k < 2; ++k) dst[m][k] = *(const LAS bf16x8*)(lds + PG8_SA(b, h) + aoff + m * 2048 + k * 1024); } while (0)
; #define PG8_MMA(ai, bj, At, Bt) do { __builtin_amdgcn_s_setprio(1); _Pragma("unroll") for (int m = 0; m < 4; ++m) _Pragma("unroll") for (int n = 0; n < 2; ++n) _Pragma("unroll") for (int k = 0; k < 2; ++k) \
;         acc[ai][bj][m][n] = __builtin_amdgcn_mfma_f32_16x16x32_bf16(Bt[n][k], At[m][k], acc[ai][bj][m][n], 0, 0, 0); __builtin_amdgcn_s_setprio(0); } while (0)
; #define PG8_WAIT_V(n) asm volatile("s_waitcnt vmcnt(" #n ")" ::: "memory")
; #define PG8_WAIT_L(n) asm volatile("s_waitcnt lgkmcnt(" #n ")" ::: "memory")
; #define PG8_BAR __builtin_amdgcn_s_barrier()
; #define PG8_SCHED __builtin_amdgcn_sched_barrier(0)
; template <class Epi>
; __device__ __forceinline__ void gemm_phase(LAS unsigned char* lds, const Gemm g, const StaticOrder& S, const Epi& E) {
;     ...
;             PG8_LDA(At, 1, 1); PG8_STAGE(PG8_SA(1, 0), a3, voffA);
;             PG8_BAR; PG8_WAIT_L(0); PG8_MMA(1, 0, At, B0); PG8_BAR; PG8_SCHED;
;             PG8_STAGE(PG8_SB(1, 1), b3 + hstep, voffB);
;             PG8_WAIT_V(6); PG8_BAR; PG8_MMA(1, 1, At, B1); PG8_BAR;
;         }
	s_waitcnt lgkmcnt(0)
	s_waitcnt lgkmcnt(0)
	v_mfma_f32_16x16x32_bf16 v[60:63], v[144:147], v[170:173], v[60:63]
	v_mfma_f32_16x16x32_bf16 v[56:59], v[162:165], v[170:173], v[56:59]
	v_mfma_f32_16x16x32_bf16 v[52:55], v[144:147], v[178:181], v[52:55]
	v_mfma_f32_16x16x32_bf16 v[44:47], v[162:165], v[178:181], v[44:47]
	v_mfma_f32_16x16x32_bf16 v[36:39], v[144:147], v[186:189], v[36:39]
	v_mfma_f32_16x16x32_bf16 v[28:31], v[162:165], v[186:189], v[28:31]
	v_mfma_f32_16x16x32_bf16 v[20:23], v[144:147], v[194:197], v[20:23]
	v_mfma_f32_16x16x32_bf16 v[12:15], v[162:165], v[194:197], v[12:15]
	v_mfma_f32_16x16x32_bf16 v[60:63], v[158:161], v[174:177], v[60:63]
	v_mfma_f32_16x16x32_bf16 v[56:59], v[166:169], v[174:177], v[56:59]
	v_mfma_f32_16x16x32_bf16 v[52:55], v[158:161], v[182:185], v[52:55]
	v_mfma_f32_16x16x32_bf16 v[44:47], v[166:169], v[182:185], v[44:47]
	v_mfma_f32_16x16x32_bf16 v[36:39], v[158:161], v[190:193], v[36:39]
	v_mfma_f32_16x16x32_bf16 v[28:31], v[166:169], v[190:193], v[28:31]
	v_mfma_f32_16x16x32_bf16 v[20:23], v[158:161], v[198:201], v[20:23]
	v_mfma_f32_16x16x32_bf16 v[12:15], v[166:169], v[198:201], v[12:15]
	s_barrier
	s_add_u32 s24, s24, 0x80080
	s_addc_u32 s25, s25, 0
	s_add_i32 s26, s26, s29
	v_lshl_add_u64 v[144:145], s[24:25], 0, v[130:131]
	s_mov_b32 m0, s26
	s_nop 0
	global_load_lds_dwordx4 v[144:145], off
	v_lshl_add_u64 v[144:145], s[24:25], 0, v[134:135]
	s_add_i32 m0, s26, 0x2000
	s_nop 0
	global_load_lds_dwordx4 v[144:145], off
	s_waitcnt vmcnt(6)
	s_barrier
	v_mfma_f32_16x16x32_bf16 v[48:51], v[202:205], v[170:173], v[48:51]
	v_mfma_f32_16x16x32_bf16 v[40:43], v[210:213], v[170:173], v[40:43]
	v_mfma_f32_16x16x32_bf16 v[32:35], v[202:205], v[178:181], v[32:35]
	v_mfma_f32_16x16x32_bf16 v[24:27], v[210:213], v[178:181], v[24:27]
	v_mfma_f32_16x16x32_bf16 v[16:19], v[202:205], v[186:189], v[16:19]
	v_mfma_f32_16x16x32_bf16 v[8:11], v[210:213], v[186:189], v[8:11]
	v_mfma_f32_16x16x32_bf16 v[4:7], v[202:205], v[194:197], v[4:7]
	v_mfma_f32_16x16x32_bf16 v[0:3], v[210:213], v[194:197], v[0:3]
	v_mfma_f32_16x16x32_bf16 v[48:51], v[206:209], v[174:177], v[48:51]
	v_mfma_f32_16x16x32_bf16 v[40:43], v[216:219], v[174:177], v[40:43]
	v_mfma_f32_16x16x32_bf16 v[32:35], v[206:209], v[182:185], v[32:35]
	v_mfma_f32_16x16x32_bf16 v[24:27], v[216:219], v[182:185], v[24:27]
	v_mfma_f32_16x16x32_bf16 v[16:19], v[206:209], v[190:193], v[16:19]
	v_mfma_f32_16x16x32_bf16 v[8:11], v[216:219], v[190:193], v[8:11]
	v_mfma_f32_16x16x32_bf16 v[4:7], v[206:209], v[198:201], v[4:7]
	v_mfma_f32_16x16x32_bf16 v[0:3], v[216:219], v[198:201], v[0:3]
	s_add_i32 s77, s77, 2
	s_add_u32 s22, s22, 0x100
	s_addc_u32 s23, s23, 0
	s_add_u32 s75, s75, 0x100
	s_addc_u32 s76, s76, 0
	s_cmp_gt_u32 s77, 29
	s_barrier
	s_cbranch_scc0 .LBB0_136
; __device__ __forceinline__ u32x4 pack8(const f32x4 v0, const f32x4 v1) { u32x4 w; w.x = cvt_pk_bf16(v0[0], v0[1]); w.y = cvt_pk_bf16(v0[2], v0[3]); w.z = cvt_pk_bf16(v1[0], v1[1]); w.w = cvt_pk_bf16(v1[2], v1[3]); return w; }
;     __device__ __forceinline__ void operator()(const AccT& acc, const pg8::Unit& u, int wr, int wc, int fr, int fq) const {
;         const int row0 = u.pm * 256 + wr * 64 + fr, col0 = u.pn * 256 + wc * 32 + 8 * fq;
; #pragma unroll
;         for (int ai = 0; ai < 2; ++ai)
; #pragma unroll
;             for (int m = 0; m < 4; ++m) { bf16_t* rowp = O + (size_t)(row0 + ai * 128 + m * 16) * NPROJ + col0;
; #pragma unroll
;                 for (int bj = 0; bj < 2; ++bj) *(u32x4*)(rowp + bj * 128) = pack8(acc[ai][bj][m][0], acc[ai][bj][m][1]); }
;     }
	v_lshl_or_b32 v146, s72, 8, v153
	v_lshl_add_u32 v157, s16, 8, v151
	v_ashrrev_i32_e32 v147, 31, v146
	v_mov_b64_e32 v[144:145], s[0:1]
	v_mad_i64_i32 v[158:159], s[22:23], v157, s71, v[144:145]
	v_lshlrev_b64 v[146:147], 1, v[146:147]
	v_lshl_add_u64 v[158:159], v[158:159], 0, v[146:147]
	v_cvt_pk_bf16_f32 v124, v124, v125
	v_cvt_pk_bf16_f32 v125, v126, v127
	v_cvt_pk_bf16_f32 v126, v120, v121
	v_cvt_pk_bf16_f32 v127, v122, v123
	global_store_dwordx4 v[158:159], v[124:127], off sc1
	v_cvt_pk_bf16_f32 v112, v112, v113
	v_cvt_pk_bf16_f32 v113, v114, v115
	v_cvt_pk_bf16_f32 v114, v104, v105
	v_or_b32_e32 v104, 16, v157
	v_mad_i64_i32 v[104:105], s[22:23], v104, s71, v[144:145]
	v_cvt_pk_bf16_f32 v115, v106, v107
	global_store_dwordx4 v[158:159], v[112:115], off offset:256 sc1
	s_and_b64 vcc, exec, s[2:3]
	s_mov_b32 s72, s8
	v_lshl_add_u64 v[112:113], v[104:105], 0, v[146:147]
	v_cvt_pk_bf16_f32 v104, v116, v117
	v_cvt_pk_bf16_f32 v105, v118, v119
	v_cvt_pk_bf16_f32 v106, v108, v109
	v_cvt_pk_bf16_f32 v107, v110, v111
	global_store_dwordx4 v[112:113], v[104:107], off sc1
	v_cvt_pk_bf16_f32 v96, v96, v97
	v_cvt_pk_bf16_f32 v97, v98, v99
	v_cvt_pk_bf16_f32 v98, v88, v89
	v_or_b32_e32 v88, 32, v157
	v_mad_i64_i32 v[88:89], s[22:23], v88, s71, v[144:145]
	v_cvt_pk_bf16_f32 v99, v90, v91
	global_store_dwordx4 v[112:113], v[96:99], off offset:256 sc1
	s_mov_b32 s16, s10
	s_mov_b64 s[24:25], s[20:21]
	v_lshl_add_u64 v[96:97], v[88:89], 0, v[146:147]
	v_cvt_pk_bf16_f32 v88, v100, v101
	v_cvt_pk_bf16_f32 v89, v102, v103
	v_cvt_pk_bf16_f32 v90, v92, v93
	v_cvt_pk_bf16_f32 v91, v94, v95
	global_store_dwordx4 v[96:97], v[88:91], off sc1
	v_cvt_pk_bf16_f32 v80, v80, v81
	v_cvt_pk_bf16_f32 v81, v82, v83
	v_cvt_pk_bf16_f32 v82, v72, v73
	v_or_b32_e32 v72, 48, v157
	v_mad_i64_i32 v[72:73], s[22:23], v72, s71, v[144:145]
	v_cvt_pk_bf16_f32 v83, v74, v75
	global_store_dwordx4 v[96:97], v[80:83], off offset:256 sc1
	s_nop 1
	v_lshl_add_u64 v[80:81], v[72:73], 0, v[146:147]
	v_cvt_pk_bf16_f32 v72, v84, v85
	v_cvt_pk_bf16_f32 v73, v86, v87
	v_cvt_pk_bf16_f32 v74, v76, v77
	v_cvt_pk_bf16_f32 v75, v78, v79
	global_store_dwordx4 v[80:81], v[72:75], off sc1
	v_cvt_pk_bf16_f32 v68, v68, v69
	v_cvt_pk_bf16_f32 v69, v70, v71
	v_cvt_pk_bf16_f32 v70, v64, v65
	v_add_u32_e32 v64, 0x80, v157
	v_mad_i64_i32 v[64:65], s[22:23], v64, s71, v[144:145]
	v_lshl_add_u64 v[64:65], v[64:65], 0, v[146:147]
	v_cvt_pk_bf16_f32 v71, v66, v67
	global_store_dwordx4 v[80:81], v[68:71], off offset:256 sc1
	v_cvt_pk_bf16_f32 v60, v60, v61
	v_cvt_pk_bf16_f32 v61, v62, v63
	v_cvt_pk_bf16_f32 v62, v56, v57
	v_cvt_pk_bf16_f32 v63, v58, v59
	global_store_dwordx4 v[64:65], v[60:63], off sc1
	v_cvt_pk_bf16_f32 v48, v48, v49
	v_cvt_pk_bf16_f32 v49, v50, v51
	v_cvt_pk_bf16_f32 v50, v40, v41
	v_add_u32_e32 v40, 0x90, v157
	v_mad_i64_i32 v[40:41], s[22:23], v40, s71, v[144:145]
	v_cvt_pk_bf16_f32 v51, v42, v43
	global_store_dwordx4 v[64:65], v[48:51], off offset:256 sc1
	s_nop 1
	v_lshl_add_u64 v[48:49], v[40:41], 0, v[146:147]
	v_cvt_pk_bf16_f32 v40, v52, v53
	v_cvt_pk_bf16_f32 v41, v54, v55
	v_cvt_pk_bf16_f32 v42, v44, v45
	v_cvt_pk_bf16_f32 v43, v46, v47
	global_store_dwordx4 v[48:49], v[40:43], off sc1
	v_cvt_pk_bf16_f32 v32, v32, v33
	v_cvt_pk_bf16_f32 v33, v34, v35
	v_cvt_pk_bf16_f32 v34, v24, v25
	v_add_u32_e32 v24, 0xa0, v157
	v_mad_i64_i32 v[24:25], s[22:23], v24, s71, v[144:145]
	v_cvt_pk_bf16_f32 v35, v26, v27
	global_store_dwordx4 v[48:49], v[32:35], off offset:256 sc1
	s_nop 1
	v_lshl_add_u64 v[32:33], v[24:25], 0, v[146:147]
	v_cvt_pk_bf16_f32 v24, v36, v37
	v_cvt_pk_bf16_f32 v25, v38, v39
	v_cvt_pk_bf16_f32 v26, v28, v29
	v_cvt_pk_bf16_f32 v27, v30, v31
	global_store_dwordx4 v[32:33], v[24:27], off sc1
	v_cvt_pk_bf16_f32 v16, v16, v17
	v_cvt_pk_bf16_f32 v17, v18, v19
	v_cvt_pk_bf16_f32 v18, v8, v9
	v_add_u32_e32 v8, 0xb0, v157
	v_mad_i64_i32 v[8:9], s[22:23], v8, s71, v[144:145]
	v_cvt_pk_bf16_f32 v19, v10, v11
	global_store_dwordx4 v[32:33], v[16:19], off offset:256 sc1
	s_mov_b64 s[22:23], s[18:19]
	s_nop 0
	v_lshl_add_u64 v[16:17], v[8:9], 0, v[146:147]
	v_cvt_pk_bf16_f32 v8, v20, v21
	v_cvt_pk_bf16_f32 v9, v22, v23
	v_cvt_pk_bf16_f32 v10, v12, v13
	v_cvt_pk_bf16_f32 v11, v14, v15
	global_store_dwordx4 v[16:17], v[8:11], off sc1
	v_cvt_pk_bf16_f32 v4, v4, v5
	v_cvt_pk_bf16_f32 v5, v6, v7
	v_cvt_pk_bf16_f32 v6, v0, v1
	v_cvt_pk_bf16_f32 v7, v2, v3
	global_store_dwordx4 v[16:17], v[4:7], off offset:256 sc1
	s_cbranch_vccz .LBB0_129
	s_waitcnt vmcnt(0)
	s_cmpk_gt_u32 s28, 0xff
	s_cbranch_scc1 .LBB0_140
	s_barrier

; __device__ __forceinline__ unsigned cvt_pk_bf16(float lo, float hi) { unsigned r; asm volatile("v_cvt_pk_bf16_f32 %0, %1, %2" : "=v"(r) : "v"(lo), "v"(hi)); return r; }
; __device__ __forceinline__ void convert_dynamic(const Params& P, unsigned char* shm, unsigned* ctr, int t0, int t1) {
;     ...
;         for (int h = 0; h < 4; ++h) { d[h] = tile_desc(P, t + h < t1 ? t + h : t);
; #pragma unroll
;             for (int i = 0; i < 4; ++i) v[h][i] = *(const f32x4*)(d[h].src + (size_t)(r0 + 32 * i) * d[h].ld + c4 * 4); }
; #pragma unroll
;         for (int h = 0; h < 4; ++h) {
;             if (t + h < t1) {
; #pragma unroll
;                 for (int i = 0; i < 4; ++i) { float* tp = tile + (r0 + 32 * i) * 65 + c4 * 4; tp[0] = v[h][i][0]; tp[1] = v[h][i][1]; tp[2] = v[h][i][2]; tp[3] = v[h][i][3]; }
;                 __syncthreads();
;                 { const int n = tid >> 3, kc = tid & 7; float x[16];
; #pragma unroll
;                   for (int jj = 0; jj < 8; ++jj) { x[jj] = tile[(kc * 8 + jj) * 65 + n]; x[8 + jj] = tile[(64 + kc * 8 + jj) * 65 + n]; }
;                   u32x4 w0, w1; w0.x = cvt_pk_bf16(x[0], x[1]); w0.y = cvt_pk_bf16(x[2], x[3]); w0.z = cvt_pk_bf16(x[4], x[5]); w0.w = cvt_pk_bf16(x[6], x[7]);
;                   w1.x = cvt_pk_bf16(x[8], x[9]); w1.y = cvt_pk_bf16(x[10], x[11]); w1.z = cvt_pk_bf16(x[12], x[13]); w1.w = cvt_pk_bf16(x[14], x[15]);
;                   bf16_t* dp = d[h].dst + (size_t)n * d[h].ldd + kc * 8; *(u32x4*)dp = w0; *(u32x4*)(dp + 64) = w1; }
;                 __syncthreads();
.LBB0_229:
	s_or_b64 exec, exec, s[30:31]
	v_lshl_add_u64 v[58:59], v[48:49], 0, v[66:67]
	v_mul_u32_u24_e32 v48, v56, v149
	v_lshlrev_b32_e32 v66, 2, v48
	v_mul_hi_u32_u24_e32 v51, v56, v65
	v_mul_u32_u24_e32 v50, v56, v65
	v_mul_hi_u32_u24_e32 v61, v56, v69
	v_mul_u32_u24_e32 v60, v56, v69
	v_mul_hi_u32_u24_e32 v57, v56, v86
	v_mul_u32_u24_e32 v56, v56, v86
	v_lshl_add_u64 v[48:49], v[58:59], 0, v[66:67]
	v_lshl_add_u64 v[50:51], v[50:51], 2, v[58:59]
	v_lshl_add_u64 v[60:61], v[60:61], 2, v[58:59]
	v_lshl_add_u64 v[56:57], v[56:57], 2, v[58:59]
	global_load_dwordx4 v[52:55], v[48:49], off
	s_nop 0
	global_load_dwordx4 v[48:51], v[50:51], off
	s_nop 0
	global_load_dwordx4 v[60:63], v[60:61], off
	s_nop 0
	global_load_dwordx4 v[56:59], v[56:57], off
	s_waitcnt vmcnt(15)
	ds_write2_b32 v90, v4, v5 offset1:1
	ds_write2_b32 v90, v6, v7 offset0:2 offset1:3
	v_add_u32_e32 v4, 0x2080, v90
	s_waitcnt vmcnt(14)
	ds_write2_b32 v4, v0, v1 offset1:1
	v_add_u32_e32 v0, 0x2088, v90
	ds_write2_b32 v0, v2, v3 offset1:1
	v_add_u32_e32 v1, 0x4100, v90
	v_add_u32_e32 v2, 0x4108, v90
	v_add_u32_e32 v5, 0x6180, v90
	v_add_u32_e32 v6, 0x6188, v90
	v_add_u32_e32 v3, 0x400, v87
	s_waitcnt vmcnt(13)
	ds_write2_b32 v1, v12, v13 offset1:1
	ds_write2_b32 v2, v14, v15 offset1:1
	s_waitcnt vmcnt(12)
	ds_write2_b32 v5, v8, v9 offset1:1
	ds_write2_b32 v6, v10, v11 offset1:1
	s_waitcnt lgkmcnt(0)
	s_barrier
	ds_read2_b32 v[12:13], v87 offset1:65
	ds_read2_b32 v[14:15], v87 offset0:130 offset1:195
	ds_read2_b32 v[92:93], v3 offset0:4 offset1:69
	ds_read2_b32 v[94:95], v3 offset0:134 offset1:199
	v_mul_u32_u24_e32 v11, v72, v148
	v_lshlrev_b32_e32 v66, 1, v11
	v_add_u32_e32 v7, 0x4000, v88
	v_add_u32_e32 v8, 0x4200, v88
	v_add_u32_e32 v9, 0x4400, v88
	v_add_u32_e32 v10, 0x4600, v88
	v_lshl_add_u64 v[70:71], v[70:71], 0, v[66:67]
	v_lshlrev_b32_e32 v66, 1, v68
	ds_read2_b32 v[96:97], v7 offset0:64 offset1:129
	ds_read2_b32 v[98:99], v8 offset0:66 offset1:131
	ds_read2_b32 v[100:101], v9 offset0:68 offset1:133
	ds_read2_b32 v[102:103], v10 offset0:70 offset1:135
	s_waitcnt lgkmcnt(7)
	v_cvt_pk_bf16_f32 v12, v12, v13
	s_waitcnt lgkmcnt(6)
	v_cvt_pk_bf16_f32 v13, v14, v15
	s_waitcnt lgkmcnt(5)
	v_cvt_pk_bf16_f32 v14, v92, v93
	s_waitcnt lgkmcnt(4)
	v_cvt_pk_bf16_f32 v15, v94, v95
	v_lshl_add_u64 v[70:71], v[70:71], 0, v[66:67]
	s_waitcnt lgkmcnt(3)
	v_cvt_pk_bf16_f32 v92, v96, v97
	s_waitcnt lgkmcnt(2)
	v_cvt_pk_bf16_f32 v93, v98, v99
	s_waitcnt lgkmcnt(1)
	v_cvt_pk_bf16_f32 v94, v100, v101
	s_waitcnt lgkmcnt(0)
	v_cvt_pk_bf16_f32 v95, v102, v103
	global_store_dwordx4 v[70:71], v[12:15], off sc1
	global_store_dwordx4 v[70:71], v[92:95], off offset:128 sc1
	s_barrier
	s_and_saveexec_b64 s[0:1], vcc
	s_cbranch_execnz .LBB0_232
	s_or_b64 exec, exec, s[0:1]
	s_and_saveexec_b64 s[0:1], s[2:3]
	s_cbranch_execnz .LBB0_233

; __device__ __forceinline__ unsigned cvt_pk_bf16(float lo, float hi) { unsigned r; asm volatile("v_cvt_pk_bf16_f32 %0, %1, %2" : "=v"(r) : "v"(lo), "v"(hi)); return r; }
; __device__ __forceinline__ void convert_dynamic(const Params& P, unsigned char* shm, unsigned* ctr, int t0, int t1) {
;     ...
;         for (int h = 0; h < 4; ++h) {
;             if (t + h < t1) {
; #pragma unroll
;                 for (int i = 0; i < 4; ++i) { float* tp = tile + (r0 + 32 * i) * 65 + c4 * 4; tp[0] = v[h][i][0]; tp[1] = v[h][i][1]; tp[2] = v[h][i][2]; tp[3] = v[h][i][3]; }
;                 __syncthreads();
;                 { const int n = tid >> 3, kc = tid & 7; float x[16];
; #pragma unroll
;                   for (int jj = 0; jj < 8; ++jj) { x[jj] = tile[(kc * 8 + jj) * 65 + n]; x[8 + jj] = tile[(64 + kc * 8 + jj) * 65 + n]; }
;                   u32x4 w0, w1; w0.x = cvt_pk_bf16(x[0], x[1]); w0.y = cvt_pk_bf16(x[2], x[3]); w0.z = cvt_pk_bf16(x[4], x[5]); w0.w = cvt_pk_bf16(x[6], x[7]);
;                   w1.x = cvt_pk_bf16(x[8], x[9]); w1.y = cvt_pk_bf16(x[10], x[11]); w1.z = cvt_pk_bf16(x[12], x[13]); w1.w = cvt_pk_bf16(x[14], x[15]);
;                   bf16_t* dp = d[h].dst + (size_t)n * d[h].ldd + kc * 8; *(u32x4*)dp = w0; *(u32x4*)(dp + 64) = w1; }
;                 __syncthreads();
.LBB0_232:
	s_waitcnt vmcnt(13)
	ds_write2_b32 v90, v20, v21 offset1:1
	ds_write2_b32 v90, v22, v23 offset0:2 offset1:3
	s_waitcnt vmcnt(12)
	ds_write2_b32 v4, v16, v17 offset1:1
	ds_write2_b32 v0, v18, v19 offset1:1
	s_waitcnt vmcnt(11)
	ds_write2_b32 v1, v28, v29 offset1:1
	ds_write2_b32 v2, v30, v31 offset1:1
	s_waitcnt vmcnt(10)
	ds_write2_b32 v5, v24, v25 offset1:1
	ds_write2_b32 v6, v26, v27 offset1:1
	s_waitcnt lgkmcnt(0)
	s_barrier
	ds_read2_b32 v[12:13], v87 offset1:65
	ds_read2_b32 v[14:15], v87 offset0:130 offset1:195
	ds_read2_b32 v[16:17], v3 offset0:4 offset1:69
	ds_read2_b32 v[18:19], v3 offset0:134 offset1:199
	ds_read2_b32 v[20:21], v7 offset0:64 offset1:129
	ds_read2_b32 v[22:23], v8 offset0:66 offset1:131
	ds_read2_b32 v[24:25], v9 offset0:68 offset1:133
	ds_read2_b32 v[26:27], v10 offset0:70 offset1:135
	v_mul_u32_u24_e32 v11, v76, v148
	s_waitcnt lgkmcnt(7)
	v_cvt_pk_bf16_f32 v12, v12, v13
	s_waitcnt lgkmcnt(6)
	v_cvt_pk_bf16_f32 v13, v14, v15
	s_waitcnt lgkmcnt(5)
	v_cvt_pk_bf16_f32 v14, v16, v17
	s_waitcnt lgkmcnt(4)
	v_cvt_pk_bf16_f32 v15, v18, v19
	s_waitcnt lgkmcnt(3)
	v_cvt_pk_bf16_f32 v16, v20, v21
	v_lshlrev_b32_e32 v20, 1, v11
	v_mov_b32_e32 v21, v67
	v_lshl_add_u64 v[20:21], v[74:75], 0, v[20:21]
	v_lshl_add_u64 v[20:21], v[20:21], 0, v[66:67]
	s_waitcnt lgkmcnt(2)
	v_cvt_pk_bf16_f32 v17, v22, v23
	s_waitcnt lgkmcnt(1)
	v_cvt_pk_bf16_f32 v18, v24, v25
	s_waitcnt lgkmcnt(0)
	v_cvt_pk_bf16_f32 v19, v26, v27
	global_store_dwordx4 v[20:21], v[12:15], off sc1
	global_store_dwordx4 v[20:21], v[16:19], off offset:128 sc1
	s_barrier
	s_or_b64 exec, exec, s[0:1]
	s_and_saveexec_b64 s[0:1], s[2:3]
	s_cbranch_execz .LBB0_231
.LBB0_233:
	s_waitcnt vmcnt(9)
	ds_write2_b32 v90, v36, v37 offset1:1
	ds_write2_b32 v90, v38, v39 offset0:2 offset1:3
	s_waitcnt vmcnt(8)
	ds_write2_b32 v4, v32, v33 offset1:1
	ds_write2_b32 v0, v34, v35 offset1:1
	s_waitcnt vmcnt(7)
	ds_write2_b32 v1, v44, v45 offset1:1
	ds_write2_b32 v2, v46, v47 offset1:1
	s_waitcnt vmcnt(6)
	ds_write2_b32 v5, v40, v41 offset1:1
	ds_write2_b32 v6, v42, v43 offset1:1
	s_waitcnt lgkmcnt(0)
	s_barrier
	ds_read2_b32 v[12:13], v87 offset1:65
	ds_read2_b32 v[14:15], v87 offset0:130 offset1:195
	ds_read2_b32 v[16:17], v3 offset0:4 offset1:69
	ds_read2_b32 v[18:19], v3 offset0:134 offset1:199
	ds_read2_b32 v[20:21], v7 offset0:64 offset1:129
	ds_read2_b32 v[22:23], v8 offset0:66 offset1:131
	ds_read2_b32 v[24:25], v9 offset0:68 offset1:133
	ds_read2_b32 v[26:27], v10 offset0:70 offset1:135
	v_mul_u32_u24_e32 v11, v80, v148
	s_waitcnt lgkmcnt(7)
	v_cvt_pk_bf16_f32 v12, v12, v13
	s_waitcnt lgkmcnt(6)
	v_cvt_pk_bf16_f32 v13, v14, v15
	s_waitcnt lgkmcnt(5)
	v_cvt_pk_bf16_f32 v14, v16, v17
	s_waitcnt lgkmcnt(4)
	v_cvt_pk_bf16_f32 v15, v18, v19
	s_waitcnt lgkmcnt(3)
	v_cvt_pk_bf16_f32 v16, v20, v21
	v_lshlrev_b32_e32 v20, 1, v11
	v_mov_b32_e32 v21, v67
	v_lshl_add_u64 v[20:21], v[78:79], 0, v[20:21]
	v_lshl_add_u64 v[20:21], v[20:21], 0, v[66:67]
	s_waitcnt lgkmcnt(2)
	v_cvt_pk_bf16_f32 v17, v22, v23
	s_waitcnt lgkmcnt(1)
	v_cvt_pk_bf16_f32 v18, v24, v25
	s_waitcnt lgkmcnt(0)
	v_cvt_pk_bf16_f32 v19, v26, v27
	global_store_dwordx4 v[20:21], v[12:15], off sc1
	global_store_dwordx4 v[20:21], v[16:19], off offset:128 sc1
	s_barrier
	s_or_b64 exec, exec, s[0:1]
	s_and_saveexec_b64 s[0:1], s[4:5]
	s_xor_b64 s[0:1], exec, s[0:1]
	s_cbranch_execz .LBB0_142
.LBB0_234:
	s_waitcnt vmcnt(5)
	ds_write2_b32 v90, v52, v53 offset1:1
	ds_write2_b32 v90, v54, v55 offset0:2 offset1:3
	s_waitcnt vmcnt(4)
	ds_write2_b32 v4, v48, v49 offset1:1
	ds_write2_b32 v0, v50, v51 offset1:1
	s_waitcnt vmcnt(3)
	ds_write2_b32 v1, v60, v61 offset1:1
	ds_write2_b32 v2, v62, v63 offset1:1
	s_waitcnt vmcnt(2)
	ds_write2_b32 v5, v56, v57 offset1:1
	ds_write2_b32 v6, v58, v59 offset1:1
	s_waitcnt lgkmcnt(0)
	s_barrier
	ds_read2_b32 v[0:1], v87 offset1:65
	ds_read2_b32 v[4:5], v87 offset0:130 offset1:195
	ds_read2_b32 v[12:13], v3 offset0:4 offset1:69
	ds_read2_b32 v[14:15], v3 offset0:134 offset1:199
	ds_read2_b32 v[6:7], v7 offset0:64 offset1:129
	ds_read2_b32 v[16:17], v8 offset0:66 offset1:131
	ds_read2_b32 v[8:9], v9 offset0:68 offset1:133
	ds_read2_b32 v[10:11], v10 offset0:70 offset1:135
	s_waitcnt lgkmcnt(7)
	v_cvt_pk_bf16_f32 v0, v0, v1
	s_waitcnt lgkmcnt(6)
	v_cvt_pk_bf16_f32 v1, v4, v5
	s_waitcnt lgkmcnt(5)
	v_cvt_pk_bf16_f32 v2, v12, v13
	s_waitcnt lgkmcnt(4)
	v_cvt_pk_bf16_f32 v3, v14, v15
	s_waitcnt lgkmcnt(3)
	v_cvt_pk_bf16_f32 v4, v6, v7
	s_waitcnt lgkmcnt(2)
	v_cvt_pk_bf16_f32 v5, v16, v17
	s_waitcnt lgkmcnt(1)
	v_cvt_pk_bf16_f32 v6, v8, v9
	v_mul_u32_u24_e32 v8, v84, v148
	v_lshlrev_b32_e32 v8, 1, v8
	v_mov_b32_e32 v9, v67
	v_lshl_add_u64 v[8:9], v[82:83], 0, v[8:9]
	v_lshl_add_u64 v[8:9], v[8:9], 0, v[66:67]
	s_waitcnt lgkmcnt(0)
	v_cvt_pk_bf16_f32 v7, v10, v11
	global_store_dwordx4 v[8:9], v[0:3], off sc1
	global_store_dwordx4 v[8:9], v[4:7], off offset:128 sc1
	s_barrier
	s_branch .LBB0_142

; #define PG8_STAGE(bufoff, gbase, voff) do { _Pragma("unroll") for (int _i = 0; _i < 2; ++_i) \
;         __builtin_amdgcn_global_load_lds((const unsigned*)((const char*)(gbase) + (voff)[_i]), (LAS unsigned*)(lds + (bufoff) + ldsw + _i * 8192), 16, 0, 0); } while (0)
; #define PG8_LDA(dst, b, h) do { _Pragma("unroll") for (int m = 0; m < 4; ++m) _Pragma("unroll") for (int k = 0; k < 2; ++k) dst[m][k] = *(const LAS bf16x8*)(lds + PG8_SA(b, h) + aoff + m * 2048 + k * 1024); } while (0)
; #define PG8_LDB(dst, b, h) do { _Pragma("unroll") for (int n = 0; n < 2; ++n) _Pragma("unroll") for (int k = 0; k < 2; ++k) dst[n][k] = *(const LAS bf16x8*)(lds + PG8_SB(b, h) + boff + n * 2048 + k * 1024); } while (0)
; #define PG8_MMA(ai, bj, At, Bt) do { __builtin_amdgcn_s_setprio(1); _Pragma("unroll") for (int m = 0; m < 4; ++m) _Pragma("unroll") for (int n = 0; n < 2; ++n) _Pragma("unroll") for (int k = 0; k < 2; ++k) \
;         acc[ai][bj][m][n] = __builtin_amdgcn_mfma_f32_16x16x32_bf16(Bt[n][k], At[m][k], acc[ai][bj][m][n], 0, 0, 0); __builtin_amdgcn_s_setprio(0); } while (0)
; #define PG8_WAIT_L(n) asm volatile("s_waitcnt lgkmcnt(" #n ")" ::: "memory")
; #define PG8_BAR __builtin_amdgcn_s_barrier()
; #define PG8_SCHED __builtin_amdgcn_sched_barrier(0)
; template <class Epi>
; __device__ __forceinline__ void gemm_phase(LAS unsigned char* lds, const Gemm g, const StaticOrder& S, const Epi& E) {
;     ...
;             PG8_LDB(B0, 0, 0); PG8_SCHED; PG8_LDA(At, 0, 0); PG8_STAGE(PG8_SA(1, 1), a1 + hstep, voffA);
;             PG8_WAIT_L(8); PG8_BAR; PG8_WAIT_L(0); PG8_MMA(0, 0, At, B0); PG8_BAR; PG8_SCHED;
;             PG8_LDB(B1, 0, 1); PG8_STAGE(PG8_SB(0, 0), b2, voffB);
;             PG8_BAR; PG8_WAIT_L(0); PG8_MMA(0, 1, At, B1); PG8_BAR;
;             PG8_LDA(At, 0, 1); PG8_STAGE(PG8_SA(0, 0), a2, voffA);
;             PG8_BAR; PG8_WAIT_L(0); PG8_MMA(1, 0, At, B0); PG8_BAR; PG8_SCHED;
.LBB0_1150:
	ds_read_b128 v[154:157], v150
	ds_read_b128 v[158:161], v150 offset:1024
	ds_read_b128 v[162:165], v150 offset:2048
	ds_read_b128 v[166:169], v150 offset:3072
	s_add_u32 s24, s22, 0xfff80080
	s_addc_u32 s25, s23, -1
	s_cmp_eq_u32 s48, 28
	s_cselect_b32 s27, s11, s25
	s_cselect_b32 s26, s44, s24
	s_cselect_b32 s25, s9, s47
	s_cselect_b32 s24, s45, s46
	v_lshl_add_u64 v[202:203], s[22:23], 0, v[136:137]
	s_add_i32 m0, s21, 0xc000
	ds_read_b128 v[170:173], v151
	ds_read_b128 v[174:177], v151 offset:1024
	ds_read_b128 v[178:181], v151 offset:2048
	ds_read_b128 v[182:185], v151 offset:3072
	ds_read_b128 v[186:189], v151 offset:4096
	ds_read_b128 v[190:193], v151 offset:5120
	ds_read_b128 v[194:197], v151 offset:6144
	ds_read_b128 v[198:201], v151 offset:7168
	global_load_lds_dwordx4 v[202:203], off
	v_lshl_add_u64 v[202:203], s[22:23], 0, v[138:139]
	s_add_i32 m0, s21, 0xe000
	s_nop 0
	global_load_lds_dwordx4 v[202:203], off
	s_waitcnt lgkmcnt(8)
	s_barrier
	s_waitcnt lgkmcnt(0)
	s_waitcnt lgkmcnt(0)
	v_mfma_f32_16x16x32_bf16 v[124:127], v[154:157], v[170:173], v[124:127]
	v_mfma_f32_16x16x32_bf16 v[120:123], v[162:165], v[170:173], v[120:123]
	v_mfma_f32_16x16x32_bf16 v[108:111], v[154:157], v[178:181], v[108:111]
	v_mfma_f32_16x16x32_bf16 v[104:107], v[162:165], v[178:181], v[104:107]
	v_mfma_f32_16x16x32_bf16 v[92:95], v[154:157], v[186:189], v[92:95]
	v_mfma_f32_16x16x32_bf16 v[88:91], v[162:165], v[186:189], v[88:91]
	v_mfma_f32_16x16x32_bf16 v[76:79], v[154:157], v[194:197], v[76:79]
	v_mfma_f32_16x16x32_bf16 v[72:75], v[162:165], v[194:197], v[72:75]
	v_mfma_f32_16x16x32_bf16 v[124:127], v[158:161], v[174:177], v[124:127]
	v_mfma_f32_16x16x32_bf16 v[120:123], v[166:169], v[174:177], v[120:123]
	v_mfma_f32_16x16x32_bf16 v[108:111], v[158:161], v[182:185], v[108:111]
	v_mfma_f32_16x16x32_bf16 v[104:107], v[166:169], v[182:185], v[104:107]
	v_mfma_f32_16x16x32_bf16 v[92:95], v[158:161], v[190:193], v[92:95]
	v_mfma_f32_16x16x32_bf16 v[88:91], v[166:169], v[190:193], v[88:91]
	v_mfma_f32_16x16x32_bf16 v[76:79], v[158:161], v[198:201], v[76:79]
	v_mfma_f32_16x16x32_bf16 v[72:75], v[166:169], v[198:201], v[72:75]
	s_barrier
	s_add_i32 s49, s40, s29
	v_lshl_add_u64 v[220:221], s[24:25], 0, v[130:131]
	s_mov_b32 m0, s49
	ds_read_b128 v[202:205], v153
	ds_read_b128 v[206:209], v153 offset:1024
	ds_read_b128 v[210:213], v153 offset:2048
	ds_read_b128 v[216:219], v153 offset:3072
	global_load_lds_dwordx4 v[220:221], off
	v_lshl_add_u64 v[222:223], s[24:25], 0, v[134:135]
	s_add_i32 m0, s49, 0x2000
	s_nop 0
	global_load_lds_dwordx4 v[222:223], off
	s_barrier
	s_waitcnt lgkmcnt(0)
	s_waitcnt lgkmcnt(0)
	v_mfma_f32_16x16x32_bf16 v[116:119], v[202:205], v[170:173], v[116:119]
	v_mfma_f32_16x16x32_bf16 v[112:115], v[210:213], v[170:173], v[112:115]
	v_mfma_f32_16x16x32_bf16 v[100:103], v[202:205], v[178:181], v[100:103]
	v_mfma_f32_16x16x32_bf16 v[96:99], v[210:213], v[178:181], v[96:99]
	v_mfma_f32_16x16x32_bf16 v[84:87], v[202:205], v[186:189], v[84:87]
	v_mfma_f32_16x16x32_bf16 v[80:83], v[210:213], v[186:189], v[80:83]
	v_mfma_f32_16x16x32_bf16 v[68:71], v[202:205], v[194:197], v[68:71]
	v_mfma_f32_16x16x32_bf16 v[64:67], v[210:213], v[194:197], v[64:67]
	v_mfma_f32_16x16x32_bf16 v[116:119], v[206:209], v[174:177], v[116:119]
	v_mfma_f32_16x16x32_bf16 v[112:115], v[216:219], v[174:177], v[112:115]
	v_mfma_f32_16x16x32_bf16 v[100:103], v[206:209], v[182:185], v[100:103]
	v_mfma_f32_16x16x32_bf16 v[96:99], v[216:219], v[182:185], v[96:99]
	v_mfma_f32_16x16x32_bf16 v[84:87], v[206:209], v[190:193], v[84:87]
	v_mfma_f32_16x16x32_bf16 v[80:83], v[216:219], v[190:193], v[80:83]
	v_mfma_f32_16x16x32_bf16 v[68:71], v[206:209], v[198:201], v[68:71]
	v_mfma_f32_16x16x32_bf16 v[64:67], v[216:219], v[198:201], v[64:67]
	s_mov_b32 m0, s21
	v_lshl_add_u64 v[224:225], s[26:27], 0, v[128:129]
	s_barrier
	ds_read_b128 v[170:173], v151 offset:16384
	ds_read_b128 v[174:177], v151 offset:17408
	ds_read_b128 v[178:181], v151 offset:18432
	ds_read_b128 v[182:185], v151 offset:19456
	ds_read_b128 v[186:189], v151 offset:20480
	ds_read_b128 v[190:193], v151 offset:21504
	ds_read_b128 v[194:197], v151 offset:22528
	ds_read_b128 v[198:201], v151 offset:23552
	global_load_lds_dwordx4 v[224:225], off
	v_lshl_add_u64 v[226:227], s[26:27], 0, v[132:133]
	s_mov_b32 m0, s30
	s_nop 0
	global_load_lds_dwordx4 v[226:227], off
	s_barrier
	s_waitcnt lgkmcnt(0)
	s_waitcnt lgkmcnt(0)
	v_mfma_f32_16x16x32_bf16 v[60:63], v[154:157], v[170:173], v[60:63]
	v_mfma_f32_16x16x32_bf16 v[56:59], v[162:165], v[170:173], v[56:59]
	v_mfma_f32_16x16x32_bf16 v[44:47], v[154:157], v[178:181], v[44:47]
	v_mfma_f32_16x16x32_bf16 v[40:43], v[162:165], v[178:181], v[40:43]
	v_mfma_f32_16x16x32_bf16 v[28:31], v[154:157], v[186:189], v[28:31]
	v_mfma_f32_16x16x32_bf16 v[24:27], v[162:165], v[186:189], v[24:27]
	v_mfma_f32_16x16x32_bf16 v[12:15], v[154:157], v[194:197], v[12:15]
	v_mfma_f32_16x16x32_bf16 v[8:11], v[162:165], v[194:197], v[8:11]
	v_mfma_f32_16x16x32_bf16 v[60:63], v[158:161], v[174:177], v[60:63]
	v_mfma_f32_16x16x32_bf16 v[56:59], v[166:169], v[174:177], v[56:59]
	v_mfma_f32_16x16x32_bf16 v[44:47], v[158:161], v[182:185], v[44:47]
	v_mfma_f32_16x16x32_bf16 v[40:43], v[166:169], v[182:185], v[40:43]
	v_mfma_f32_16x16x32_bf16 v[28:31], v[158:161], v[190:193], v[28:31]
	v_mfma_f32_16x16x32_bf16 v[24:27], v[166:169], v[190:193], v[24:27]
	v_mfma_f32_16x16x32_bf16 v[12:15], v[158:161], v[198:201], v[12:15]
	v_mfma_f32_16x16x32_bf16 v[8:11], v[166:169], v[198:201], v[8:11]
	s_barrier
; #define PG8_STAGE(bufoff, gbase, voff) do { _Pragma("unroll") for (int _i = 0; _i < 2; ++_i) \
;         __builtin_amdgcn_global_load_lds((const unsigned*)((const char*)(gbase) + (voff)[_i]), (LAS unsigned*)(lds + (bufoff) + ldsw + _i * 8192), 16, 0, 0); } while (0)
; #define PG8_LDA(dst, b, h) do { _Pragma("unroll") for (int m = 0; m < 4; ++m) _Pragma("unroll") for (int k = 0; k < 2; ++k) dst[m][k] = *(const LAS bf16x8*)(lds + PG8_SA(b, h) + aoff + m * 2048 + k * 1024); } while (0)
; #define PG8_LDB(dst, b, h) do { _Pragma("unroll") for (int n = 0; n < 2; ++n) _Pragma("unroll") for (int k = 0; k < 2; ++k) dst[n][k] = *(const LAS bf16x8*)(lds + PG8_SB(b, h) + boff + n * 2048 + k * 1024); } while (0)
; #define PG8_MMA(ai, bj, At, Bt) do { __builtin_amdgcn_s_setprio(1); _Pragma("unroll") for (int m = 0; m < 4; ++m) _Pragma("unroll") for (int n = 0; n < 2; ++n) _Pragma("unroll") for (int k = 0; k < 2; ++k) \
;         acc[ai][bj][m][n] = __builtin_amdgcn_mfma_f32_16x16x32_bf16(Bt[n][k], At[m][k], acc[ai][bj][m][n], 0, 0, 0); __builtin_amdgcn_s_setprio(0); } while (0)
; #define PG8_WAIT_V(n) asm volatile("s_waitcnt vmcnt(" #n ")" ::: "memory")
; #define PG8_WAIT_L(n) asm volatile("s_waitcnt lgkmcnt(" #n ")" ::: "memory")
; #define PG8_BAR __builtin_amdgcn_s_barrier()
; #define PG8_SCHED __builtin_amdgcn_sched_barrier(0)
; template <class Epi>
; __device__ __forceinline__ void gemm_phase(LAS unsigned char* lds, const Gemm g, const StaticOrder& S, const Epi& E) {
;     ...
;             PG8_BAR; PG8_WAIT_L(0); PG8_MMA(1, 0, At, B0); PG8_BAR; PG8_SCHED;
;             PG8_STAGE(PG8_SB(0, 1), b2 + hstep, voffB);
;             PG8_WAIT_V(6); PG8_BAR; PG8_MMA(1, 1, At, B1); PG8_BAR;
;             PG8_LDB(B0, 1, 0); PG8_SCHED; PG8_LDA(At, 1, 0); PG8_STAGE(PG8_SA(0, 1), a2 + hstep, voffA);
;             PG8_WAIT_L(8); PG8_BAR; PG8_WAIT_L(0); PG8_MMA(0, 0, At, B0); PG8_BAR; PG8_SCHED;
;             PG8_LDB(B1, 1, 1); PG8_STAGE(PG8_SB(1, 0), b3, voffB);
;             PG8_BAR; PG8_WAIT_L(0); PG8_MMA(0, 1, At, B1); PG8_BAR;
;             PG8_LDA(At, 1, 1); PG8_STAGE(PG8_SA(1, 0), a3, voffA);
	s_add_u32 s50, s24, 0x80000
	s_addc_u32 s51, s25, 0
	s_add_i32 s49, s41, s29
	v_lshl_add_u64 v[154:155], s[50:51], 0, v[130:131]
	s_mov_b32 m0, s49
	s_nop 0
	global_load_lds_dwordx4 v[154:155], off
	v_lshl_add_u64 v[154:155], s[50:51], 0, v[134:135]
	s_add_i32 m0, s49, 0x2000
	s_nop 0
	global_load_lds_dwordx4 v[154:155], off
	s_waitcnt vmcnt(6)
	s_barrier
	v_mfma_f32_16x16x32_bf16 v[52:55], v[202:205], v[170:173], v[52:55]
	v_mfma_f32_16x16x32_bf16 v[48:51], v[210:213], v[170:173], v[48:51]
	v_mfma_f32_16x16x32_bf16 v[36:39], v[202:205], v[178:181], v[36:39]
	v_mfma_f32_16x16x32_bf16 v[32:35], v[210:213], v[178:181], v[32:35]
	v_mfma_f32_16x16x32_bf16 v[20:23], v[202:205], v[186:189], v[20:23]
	v_mfma_f32_16x16x32_bf16 v[16:19], v[210:213], v[186:189], v[16:19]
	v_mfma_f32_16x16x32_bf16 v[4:7], v[202:205], v[194:197], v[4:7]
	v_mfma_f32_16x16x32_bf16 v[0:3], v[210:213], v[194:197], v[0:3]
	v_mfma_f32_16x16x32_bf16 v[52:55], v[206:209], v[174:177], v[52:55]
	v_mfma_f32_16x16x32_bf16 v[48:51], v[216:219], v[174:177], v[48:51]
	v_mfma_f32_16x16x32_bf16 v[36:39], v[206:209], v[182:185], v[36:39]
	v_mfma_f32_16x16x32_bf16 v[32:35], v[216:219], v[182:185], v[32:35]
	v_mfma_f32_16x16x32_bf16 v[20:23], v[206:209], v[190:193], v[20:23]
	v_mfma_f32_16x16x32_bf16 v[16:19], v[216:219], v[190:193], v[16:19]
	v_mfma_f32_16x16x32_bf16 v[4:7], v[206:209], v[198:201], v[4:7]
	v_mfma_f32_16x16x32_bf16 v[0:3], v[216:219], v[198:201], v[0:3]
	s_add_i32 s49, 0, 0x18000
	v_add_u32_e32 v166, s49, v148
	s_barrier
	ds_read_b128 v[154:157], v166
	ds_read_b128 v[158:161], v166 offset:1024
	ds_read_b128 v[162:165], v166 offset:2048
	ds_read_b128 v[166:169], v166 offset:3072
	s_add_u32 s26, s26, 0x80000
	s_addc_u32 s27, s27, 0
	s_mov_b32 m0, s31
	v_lshl_add_u64 v[202:203], s[26:27], 0, v[128:129]
	ds_read_b128 v[170:173], v151 offset:32768
	ds_read_b128 v[174:177], v151 offset:33792
	ds_read_b128 v[178:181], v151 offset:34816
	ds_read_b128 v[182:185], v151 offset:35840
	ds_read_b128 v[186:189], v151 offset:36864
	ds_read_b128 v[190:193], v151 offset:37888
	ds_read_b128 v[194:197], v151 offset:38912
	ds_read_b128 v[198:201], v151 offset:39936
	global_load_lds_dwordx4 v[202:203], off
	v_lshl_add_u64 v[202:203], s[26:27], 0, v[132:133]
	s_mov_b32 m0, s33
	s_nop 0
	global_load_lds_dwordx4 v[202:203], off
	s_waitcnt lgkmcnt(8)
	s_barrier
	s_waitcnt lgkmcnt(0)
	s_waitcnt lgkmcnt(0)
	v_mfma_f32_16x16x32_bf16 v[124:127], v[154:157], v[170:173], v[124:127]
	v_mfma_f32_16x16x32_bf16 v[120:123], v[162:165], v[170:173], v[120:123]
	v_mfma_f32_16x16x32_bf16 v[108:111], v[154:157], v[178:181], v[108:111]
	v_mfma_f32_16x16x32_bf16 v[104:107], v[162:165], v[178:181], v[104:107]
	v_mfma_f32_16x16x32_bf16 v[92:95], v[154:157], v[186:189], v[92:95]
	v_mfma_f32_16x16x32_bf16 v[88:91], v[162:165], v[186:189], v[88:91]
	v_mfma_f32_16x16x32_bf16 v[76:79], v[154:157], v[194:197], v[76:79]
	v_mfma_f32_16x16x32_bf16 v[72:75], v[162:165], v[194:197], v[72:75]
	v_mfma_f32_16x16x32_bf16 v[124:127], v[158:161], v[174:177], v[124:127]
	v_mfma_f32_16x16x32_bf16 v[120:123], v[166:169], v[174:177], v[120:123]
	v_mfma_f32_16x16x32_bf16 v[108:111], v[158:161], v[182:185], v[108:111]
	v_mfma_f32_16x16x32_bf16 v[104:107], v[166:169], v[182:185], v[104:107]
	v_mfma_f32_16x16x32_bf16 v[92:95], v[158:161], v[190:193], v[92:95]
	v_mfma_f32_16x16x32_bf16 v[88:91], v[166:169], v[190:193], v[88:91]
	v_mfma_f32_16x16x32_bf16 v[76:79], v[158:161], v[198:201], v[76:79]
	v_mfma_f32_16x16x32_bf16 v[72:75], v[166:169], v[198:201], v[72:75]
	s_barrier
	s_add_i32 s26, 0, 0x1c000
	s_add_i32 s27, s49, s29
	v_add_u32_e32 v216, s26, v148
	v_lshl_add_u64 v[220:221], v[220:221], 0, s[4:5]
	s_mov_b32 m0, s27
	ds_read_b128 v[202:205], v216
	ds_read_b128 v[206:209], v216 offset:1024
	ds_read_b128 v[210:213], v216 offset:2048
	ds_read_b128 v[216:219], v216 offset:3072
	global_load_lds_dwordx4 v[220:221], off
	v_lshl_add_u64 v[220:221], v[222:223], 0, s[4:5]
	s_add_i32 m0, s27, 0x2000
	s_nop 0
	global_load_lds_dwordx4 v[220:221], off
	s_barrier
	s_waitcnt lgkmcnt(0)
	s_waitcnt lgkmcnt(0)
	v_mfma_f32_16x16x32_bf16 v[116:119], v[202:205], v[170:173], v[116:119]
	v_mfma_f32_16x16x32_bf16 v[112:115], v[210:213], v[170:173], v[112:115]
	v_mfma_f32_16x16x32_bf16 v[100:103], v[202:205], v[178:181], v[100:103]
	v_mfma_f32_16x16x32_bf16 v[96:99], v[210:213], v[178:181], v[96:99]
	v_mfma_f32_16x16x32_bf16 v[84:87], v[202:205], v[186:189], v[84:87]
	v_mfma_f32_16x16x32_bf16 v[80:83], v[210:213], v[186:189], v[80:83]
	v_mfma_f32_16x16x32_bf16 v[68:71], v[202:205], v[194:197], v[68:71]
	v_mfma_f32_16x16x32_bf16 v[64:67], v[210:213], v[194:197], v[64:67]
	v_mfma_f32_16x16x32_bf16 v[116:119], v[206:209], v[174:177], v[116:119]
	v_mfma_f32_16x16x32_bf16 v[112:115], v[216:219], v[174:177], v[112:115]
	v_mfma_f32_16x16x32_bf16 v[100:103], v[206:209], v[182:185], v[100:103]
	v_mfma_f32_16x16x32_bf16 v[96:99], v[216:219], v[182:185], v[96:99]
	v_mfma_f32_16x16x32_bf16 v[84:87], v[206:209], v[190:193], v[84:87]
	v_mfma_f32_16x16x32_bf16 v[80:83], v[216:219], v[190:193], v[80:83]
	v_mfma_f32_16x16x32_bf16 v[68:71], v[206:209], v[198:201], v[68:71]
	v_mfma_f32_16x16x32_bf16 v[64:67], v[216:219], v[198:201], v[64:67]
	s_mov_b32 m0, s37
	v_lshl_add_u64 v[220:221], v[224:225], 0, s[4:5]
	s_barrier
	ds_read_b128 v[170:173], v151 offset:49152
	ds_read_b128 v[174:177], v151 offset:50176
	ds_read_b128 v[178:181], v151 offset:51200
	ds_read_b128 v[182:185], v151 offset:52224
	ds_read_b128 v[186:189], v151 offset:53248
	ds_read_b128 v[190:193], v151 offset:54272
	ds_read_b128 v[194:197], v151 offset:55296
	ds_read_b128 v[198:201], v151 offset:56320
	global_load_lds_dwordx4 v[220:221], off
	v_lshl_add_u64 v[220:221], v[226:227], 0, s[4:5]
	s_mov_b32 m0, s38
	s_nop 0
	global_load_lds_dwordx4 v[220:221], off
	s_barrier
; #define PG8_STAGE(bufoff, gbase, voff) do { _Pragma("unroll") for (int _i = 0; _i < 2; ++_i) \
;         __builtin_amdgcn_global_load_lds((const unsigned*)((const char*)(gbase) + (voff)[_i]), (LAS unsigned*)(lds + (bufoff) + ldsw + _i * 8192), 16, 0, 0); } while (0)
; #define PG8_LDA(dst, b, h) do { _Pragma("unroll") for (int m = 0; m < 4; ++m) _Pragma("unroll") for (int k = 0; k < 2; ++k) dst[m][k] = *(const LAS bf16x8*)(lds + PG8_SA(b, h) + aoff + m * 2048 + k * 1024); } while (0)
; #define PG8_MMA(ai, bj, At, Bt) do { __builtin_amdgcn_s_setprio(1); _Pragma("unroll") for (int m = 0; m < 4; ++m) _Pragma("unroll") for (int n = 0; n < 2; ++n) _Pragma("unroll") for (int k = 0; k < 2; ++k) \
;         acc[ai][bj][m][n] = __builtin_amdgcn_mfma_f32_16x16x32_bf16(Bt[n][k], At[m][k], acc[ai][bj][m][n], 0, 0, 0); __builtin_amdgcn_s_setprio(0); } while (0)
; #define PG8_WAIT_V(n) asm volatile("s_waitcnt vmcnt(" #n ")" ::: "memory")
; #define PG8_WAIT_L(n) asm volatile("s_waitcnt lgkmcnt(" #n ")" ::: "memory")
; #define PG8_BAR __builtin_amdgcn_s_barrier()
; #define PG8_SCHED __builtin_amdgcn_sched_barrier(0)
; __device__ __forceinline__ f32x4 sig4(const f32x4 v) { return (f32x4){sigmoidf_(v[0]), sigmoidf_(v[1]), sigmoidf_(v[2]), sigmoidf_(v[3])}; }
; template <class Epi>
; __device__ __forceinline__ void gemm_phase(LAS unsigned char* lds, const Gemm g, const StaticOrder& S, const Epi& E) {
;     ...
;             PG8_LDA(At, 1, 1); PG8_STAGE(PG8_SA(1, 0), a3, voffA);
;             PG8_BAR; PG8_WAIT_L(0); PG8_MMA(1, 0, At, B0); PG8_BAR; PG8_SCHED;
;             PG8_STAGE(PG8_SB(1, 1), b3 + hstep, voffB);
;             PG8_WAIT_V(6); PG8_BAR; PG8_MMA(1, 1, At, B1); PG8_BAR;
;         }
;     __device__ __forceinline__ void operator()(const AccT& acc, const pg8::Unit& u, int wr, int wc, int fr, int fq) const {
;         const int row0 = u.pm * 256 + wr * 64 + fr, col0 = u.pn * 128 + wc * 32 + 8 * fq;
; #pragma unroll
;         for (int ai = 0; ai < 2; ++ai)
; #pragma unroll
;             for (int m = 0; m < 4; ++m) { const int r = row0 + ai * 128 + m * 16;
;                 const f32x4 g0 = acc[ai][0][m][0], g1 = acc[ai][0][m][1];
;                 const f32x4 o0 = g0 * sig4(g0) * acc[ai][1][m][0], o1 = g1 * sig4(g1) * acc[ai][1][m][1];
;                 *(u32x4*)(O + (size_t)r * DFF + col0) = pack8(o0, o1); }
	s_waitcnt lgkmcnt(0)
	s_waitcnt lgkmcnt(0)
	v_mfma_f32_16x16x32_bf16 v[60:63], v[154:157], v[170:173], v[60:63]
	v_mfma_f32_16x16x32_bf16 v[56:59], v[162:165], v[170:173], v[56:59]
	v_mfma_f32_16x16x32_bf16 v[44:47], v[154:157], v[178:181], v[44:47]
	v_mfma_f32_16x16x32_bf16 v[40:43], v[162:165], v[178:181], v[40:43]
	v_mfma_f32_16x16x32_bf16 v[28:31], v[154:157], v[186:189], v[28:31]
	v_mfma_f32_16x16x32_bf16 v[24:27], v[162:165], v[186:189], v[24:27]
	v_mfma_f32_16x16x32_bf16 v[12:15], v[154:157], v[194:197], v[12:15]
	v_mfma_f32_16x16x32_bf16 v[8:11], v[162:165], v[194:197], v[8:11]
	v_mfma_f32_16x16x32_bf16 v[60:63], v[158:161], v[174:177], v[60:63]
	v_mfma_f32_16x16x32_bf16 v[56:59], v[166:169], v[174:177], v[56:59]
	v_mfma_f32_16x16x32_bf16 v[44:47], v[158:161], v[182:185], v[44:47]
	v_mfma_f32_16x16x32_bf16 v[40:43], v[166:169], v[182:185], v[40:43]
	v_mfma_f32_16x16x32_bf16 v[28:31], v[158:161], v[190:193], v[28:31]
	v_mfma_f32_16x16x32_bf16 v[24:27], v[166:169], v[190:193], v[24:27]
	v_mfma_f32_16x16x32_bf16 v[12:15], v[158:161], v[198:201], v[12:15]
	v_mfma_f32_16x16x32_bf16 v[8:11], v[166:169], v[198:201], v[8:11]
	s_barrier
	s_add_u32 s24, s24, 0x80080
	s_addc_u32 s25, s25, 0
	s_add_i32 s26, s26, s29
	v_lshl_add_u64 v[154:155], s[24:25], 0, v[130:131]
	s_mov_b32 m0, s26
	s_nop 0
	global_load_lds_dwordx4 v[154:155], off
	v_lshl_add_u64 v[154:155], s[24:25], 0, v[134:135]
	s_add_i32 m0, s26, 0x2000
	s_nop 0
	global_load_lds_dwordx4 v[154:155], off
	s_waitcnt vmcnt(6)
	s_barrier
	v_mfma_f32_16x16x32_bf16 v[52:55], v[202:205], v[170:173], v[52:55]
	v_mfma_f32_16x16x32_bf16 v[48:51], v[210:213], v[170:173], v[48:51]
	v_mfma_f32_16x16x32_bf16 v[36:39], v[202:205], v[178:181], v[36:39]
	v_mfma_f32_16x16x32_bf16 v[32:35], v[210:213], v[178:181], v[32:35]
	v_mfma_f32_16x16x32_bf16 v[20:23], v[202:205], v[186:189], v[20:23]
	v_mfma_f32_16x16x32_bf16 v[16:19], v[210:213], v[186:189], v[16:19]
	v_mfma_f32_16x16x32_bf16 v[4:7], v[202:205], v[194:197], v[4:7]
	v_mfma_f32_16x16x32_bf16 v[0:3], v[210:213], v[194:197], v[0:3]
	v_mfma_f32_16x16x32_bf16 v[52:55], v[206:209], v[174:177], v[52:55]
	v_mfma_f32_16x16x32_bf16 v[48:51], v[216:219], v[174:177], v[48:51]
	v_mfma_f32_16x16x32_bf16 v[36:39], v[206:209], v[182:185], v[36:39]
	v_mfma_f32_16x16x32_bf16 v[32:35], v[216:219], v[182:185], v[32:35]
	v_mfma_f32_16x16x32_bf16 v[20:23], v[206:209], v[190:193], v[20:23]
	v_mfma_f32_16x16x32_bf16 v[16:19], v[216:219], v[190:193], v[16:19]
	v_mfma_f32_16x16x32_bf16 v[4:7], v[206:209], v[198:201], v[4:7]
	v_mfma_f32_16x16x32_bf16 v[0:3], v[216:219], v[198:201], v[0:3]
	s_add_i32 s48, s48, 2
	s_add_u32 s22, s22, 0x100
	s_addc_u32 s23, s23, 0
	s_add_u32 s46, s46, 0x100
	s_addc_u32 s47, s47, 0
	s_cmp_gt_u32 s48, 29
	s_barrier
	s_cbranch_scc0 .LBB0_1150
	v_mul_f32_e32 v155, 0xbfb8aa3b, v124
	v_exp_f32_e32 v155, v155
	v_mul_f32_e32 v157, 0xbfb8aa3b, v125
	v_exp_f32_e32 v159, v157
	v_lshl_or_b32 v156, s43, 7, v149
	v_add_f32_e32 v155, 1.0, v155
	v_rcp_f32_e32 v158, v155
	v_add_f32_e32 v155, 1.0, v159
	v_mul_f32_e32 v159, 0xbfb8aa3b, v126
	v_exp_f32_e32 v160, v159
	v_mul_f32_e32 v159, 0xbfb8aa3b, v127
	v_exp_f32_e32 v161, v159
	v_rcp_f32_e32 v159, v155
	v_add_f32_e32 v155, 1.0, v160
	v_rcp_f32_e32 v160, v155
	v_add_f32_e32 v155, 1.0, v161
	v_rcp_f32_e32 v161, v155
	v_mul_f32_e32 v155, 0xbfb8aa3b, v120
	v_pk_mul_f32 v[124:125], v[124:125], v[158:159]
	v_exp_f32_e32 v155, v155
	v_mul_f32_e32 v158, 0xbfb8aa3b, v121
	v_exp_f32_e32 v159, v158
	v_pk_mul_f32 v[126:127], v[126:127], v[160:161]
	v_add_f32_e32 v155, 1.0, v155
	v_rcp_f32_e32 v158, v155
	v_add_f32_e32 v155, 1.0, v159
	v_mul_f32_e32 v159, 0xbfb8aa3b, v122
	v_exp_f32_e32 v160, v159
	v_mul_f32_e32 v159, 0xbfb8aa3b, v123
	v_exp_f32_e32 v161, v159
	v_rcp_f32_e32 v159, v155
	v_add_f32_e32 v155, 1.0, v160
	v_rcp_f32_e32 v160, v155
	v_add_f32_e32 v155, 1.0, v161
	v_rcp_f32_e32 v161, v155
	v_pk_mul_f32 v[120:121], v[120:121], v[158:159]
	v_pk_mul_f32 v[118:119], v[126:127], v[118:119]
	v_pk_mul_f32 v[116:117], v[124:125], v[116:117]
	v_pk_mul_f32 v[122:123], v[122:123], v[160:161]
	v_pk_mul_f32 v[112:113], v[120:121], v[112:113]
	v_lshl_add_u32 v154, s20, 8, v147
	v_ashrrev_i32_e32 v157, 31, v156
	v_pk_mul_f32 v[114:115], v[122:123], v[114:115]
	v_cvt_pk_bf16_f32 v116, v116, v117
	v_cvt_pk_bf16_f32 v117, v118, v119
	v_cvt_pk_bf16_f32 v118, v112, v113
	v_mov_b64_e32 v[112:113], s[0:1]
	v_cvt_pk_bf16_f32 v119, v114, v115
	v_mad_i64_i32 v[120:121], s[22:23], v154, s42, v[112:113]
	v_lshlrev_b64 v[114:115], 1, v[156:157]
	v_lshl_add_u64 v[120:121], v[120:121], 0, v[114:115]
	global_store_dwordx4 v[120:121], v[116:119], off sc1
	v_or_b32_e32 v120, 16, v154
	s_and_b64 vcc, exec, s[2:3]
	v_mul_f32_e32 v116, 0xbfb8aa3b, v108
	v_mul_f32_e32 v117, 0xbfb8aa3b, v109
	v_mul_f32_e32 v118, 0xbfb8aa3b, v110
	v_mul_f32_e32 v119, 0xbfb8aa3b, v111
	v_exp_f32_e32 v116, v116
	v_exp_f32_e32 v117, v117
	v_exp_f32_e32 v118, v118
	v_exp_f32_e32 v119, v119
	v_add_f32_e32 v116, 1.0, v116
	v_add_f32_e32 v117, 1.0, v117
	v_add_f32_e32 v118, 1.0, v118
	v_add_f32_e32 v119, 1.0, v119
	v_rcp_f32_e32 v116, v116
	v_rcp_f32_e32 v117, v117
	v_rcp_f32_e32 v118, v118
	v_rcp_f32_e32 v119, v119
	s_mov_b32 s43, s8
	v_pk_mul_f32 v[108:109], v[108:109], v[116:117]
	v_mul_f32_e32 v116, 0xbfb8aa3b, v104
	v_mul_f32_e32 v117, 0xbfb8aa3b, v105
	v_pk_mul_f32 v[110:111], v[110:111], v[118:119]
	v_mul_f32_e32 v118, 0xbfb8aa3b, v106
	v_mul_f32_e32 v119, 0xbfb8aa3b, v107
	v_exp_f32_e32 v116, v116
	v_exp_f32_e32 v117, v117
	v_exp_f32_e32 v118, v118
	v_exp_f32_e32 v119, v119
	v_add_f32_e32 v116, 1.0, v116
	v_add_f32_e32 v117, 1.0, v117
	v_add_f32_e32 v118, 1.0, v118
; __device__ __forceinline__ u32x4 pack8(const f32x4 v0, const f32x4 v1) { u32x4 w; w.x = cvt_pk_bf16(v0[0], v0[1]); w.y = cvt_pk_bf16(v0[2], v0[3]); w.z = cvt_pk_bf16(v1[0], v1[1]); w.w = cvt_pk_bf16(v1[2], v1[3]); return w; }
; __device__ __forceinline__ f32x4 sig4(const f32x4 v) { return (f32x4){sigmoidf_(v[0]), sigmoidf_(v[1]), sigmoidf_(v[2]), sigmoidf_(v[3])}; }
;     __device__ __forceinline__ void operator()(const AccT& acc, const pg8::Unit& u, int wr, int wc, int fr, int fq) const {
;         const int row0 = u.pm * 256 + wr * 64 + fr, col0 = u.pn * 128 + wc * 32 + 8 * fq;
; #pragma unroll
;         for (int ai = 0; ai < 2; ++ai)
; #pragma unroll
;             for (int m = 0; m < 4; ++m) { const int r = row0 + ai * 128 + m * 16;
;                 const f32x4 g0 = acc[ai][0][m][0], g1 = acc[ai][0][m][1];
;                 const f32x4 o0 = g0 * sig4(g0) * acc[ai][1][m][0], o1 = g1 * sig4(g1) * acc[ai][1][m][1];
;                 *(u32x4*)(O + (size_t)r * DFF + col0) = pack8(o0, o1); }
	v_add_f32_e32 v119, 1.0, v119
	v_rcp_f32_e32 v116, v116
	v_rcp_f32_e32 v117, v117
	v_rcp_f32_e32 v118, v118
	v_rcp_f32_e32 v119, v119
	v_pk_mul_f32 v[100:101], v[108:109], v[100:101]
	v_pk_mul_f32 v[104:105], v[104:105], v[116:117]
	v_pk_mul_f32 v[102:103], v[110:111], v[102:103]
	v_pk_mul_f32 v[106:107], v[106:107], v[118:119]
	s_mov_b32 s20, s10
	v_pk_mul_f32 v[106:107], v[106:107], v[98:99]
	v_pk_mul_f32 v[98:99], v[104:105], v[96:97]
	v_cvt_pk_bf16_f32 v96, v100, v101
	v_mad_i64_i32 v[100:101], s[22:23], v120, s42, v[112:113]
	v_cvt_pk_bf16_f32 v97, v102, v103
	v_cvt_pk_bf16_f32 v98, v98, v99
	v_cvt_pk_bf16_f32 v99, v106, v107
	v_lshl_add_u64 v[100:101], v[100:101], 0, v[114:115]
	global_store_dwordx4 v[100:101], v[96:99], off sc1
	v_or_b32_e32 v100, 32, v154
	s_mov_b64 s[24:25], s[18:19]
	v_mul_f32_e32 v96, 0xbfb8aa3b, v92
	v_mul_f32_e32 v97, 0xbfb8aa3b, v93
	v_mul_f32_e32 v98, 0xbfb8aa3b, v94
	v_mul_f32_e32 v99, 0xbfb8aa3b, v95
	v_exp_f32_e32 v96, v96
	v_exp_f32_e32 v97, v97
	v_exp_f32_e32 v98, v98
	v_exp_f32_e32 v99, v99
	v_add_f32_e32 v96, 1.0, v96
	v_add_f32_e32 v97, 1.0, v97
	v_add_f32_e32 v98, 1.0, v98
	v_add_f32_e32 v99, 1.0, v99
	v_rcp_f32_e32 v96, v96
	v_rcp_f32_e32 v97, v97
	v_rcp_f32_e32 v98, v98
	v_rcp_f32_e32 v99, v99
	v_pk_mul_f32 v[92:93], v[92:93], v[96:97]
	v_mul_f32_e32 v96, 0xbfb8aa3b, v88
	v_mul_f32_e32 v97, 0xbfb8aa3b, v89
	v_pk_mul_f32 v[94:95], v[94:95], v[98:99]
	v_mul_f32_e32 v98, 0xbfb8aa3b, v90
	v_mul_f32_e32 v99, 0xbfb8aa3b, v91
	v_exp_f32_e32 v96, v96
	v_exp_f32_e32 v97, v97
	v_exp_f32_e32 v98, v98
	v_exp_f32_e32 v99, v99
	v_add_f32_e32 v96, 1.0, v96
	v_add_f32_e32 v97, 1.0, v97
	v_add_f32_e32 v98, 1.0, v98
	v_add_f32_e32 v99, 1.0, v99
	v_rcp_f32_e32 v96, v96
	v_rcp_f32_e32 v97, v97
	v_rcp_f32_e32 v98, v98
	v_rcp_f32_e32 v99, v99
	v_pk_mul_f32 v[84:85], v[92:93], v[84:85]
	v_pk_mul_f32 v[88:89], v[88:89], v[96:97]
	v_pk_mul_f32 v[86:87], v[94:95], v[86:87]
	v_pk_mul_f32 v[90:91], v[90:91], v[98:99]
	s_nop 0
	v_pk_mul_f32 v[90:91], v[90:91], v[82:83]
	v_pk_mul_f32 v[82:83], v[88:89], v[80:81]
	v_cvt_pk_bf16_f32 v80, v84, v85
	v_mad_i64_i32 v[84:85], s[22:23], v100, s42, v[112:113]
	v_cvt_pk_bf16_f32 v81, v86, v87
	v_cvt_pk_bf16_f32 v82, v82, v83
	v_cvt_pk_bf16_f32 v83, v90, v91
	v_lshl_add_u64 v[84:85], v[84:85], 0, v[114:115]
	global_store_dwordx4 v[84:85], v[80:83], off sc1
	v_or_b32_e32 v84, 48, v154
	s_nop 0
	v_mul_f32_e32 v80, 0xbfb8aa3b, v76
	v_mul_f32_e32 v81, 0xbfb8aa3b, v77
	v_mul_f32_e32 v82, 0xbfb8aa3b, v78
	v_mul_f32_e32 v83, 0xbfb8aa3b, v79
	v_exp_f32_e32 v80, v80
	v_exp_f32_e32 v81, v81
	v_exp_f32_e32 v82, v82
	v_exp_f32_e32 v83, v83
	v_add_f32_e32 v80, 1.0, v80
	v_add_f32_e32 v81, 1.0, v81
	v_add_f32_e32 v82, 1.0, v82
	v_add_f32_e32 v83, 1.0, v83
	v_rcp_f32_e32 v80, v80
	v_rcp_f32_e32 v81, v81
	v_rcp_f32_e32 v82, v82
	v_rcp_f32_e32 v83, v83
	v_pk_mul_f32 v[76:77], v[76:77], v[80:81]
	v_mul_f32_e32 v80, 0xbfb8aa3b, v72
	v_mul_f32_e32 v81, 0xbfb8aa3b, v73
	v_pk_mul_f32 v[78:79], v[78:79], v[82:83]
	v_mul_f32_e32 v82, 0xbfb8aa3b, v74
	v_mul_f32_e32 v83, 0xbfb8aa3b, v75
	v_exp_f32_e32 v80, v80
	v_exp_f32_e32 v81, v81
	v_exp_f32_e32 v82, v82
	v_exp_f32_e32 v83, v83
	v_add_f32_e32 v80, 1.0, v80
	v_add_f32_e32 v81, 1.0, v81
	v_add_f32_e32 v82, 1.0, v82
	v_add_f32_e32 v83, 1.0, v83
	v_rcp_f32_e32 v80, v80
	v_rcp_f32_e32 v81, v81
	v_rcp_f32_e32 v82, v82
	v_rcp_f32_e32 v83, v83
	v_pk_mul_f32 v[68:69], v[76:77], v[68:69]
	v_pk_mul_f32 v[72:73], v[72:73], v[80:81]
	v_pk_mul_f32 v[70:71], v[78:79], v[70:71]
	v_pk_mul_f32 v[74:75], v[74:75], v[82:83]
	s_nop 0
	v_pk_mul_f32 v[74:75], v[74:75], v[66:67]
	v_pk_mul_f32 v[66:67], v[72:73], v[64:65]
	v_cvt_pk_bf16_f32 v64, v68, v69
	v_mad_i64_i32 v[68:69], s[22:23], v84, s42, v[112:113]
	v_cvt_pk_bf16_f32 v65, v70, v71
	v_cvt_pk_bf16_f32 v66, v66, v67
	v_cvt_pk_bf16_f32 v67, v74, v75
	v_lshl_add_u64 v[68:69], v[68:69], 0, v[114:115]
	global_store_dwordx4 v[68:69], v[64:67], off sc1
	v_add_u32_e32 v68, 0x80, v154
	s_nop 0
	v_mul_f32_e32 v64, 0xbfb8aa3b, v60
	v_mul_f32_e32 v65, 0xbfb8aa3b, v61
	v_mul_f32_e32 v66, 0xbfb8aa3b, v62
	v_mul_f32_e32 v67, 0xbfb8aa3b, v63
	v_exp_f32_e32 v64, v64
	v_exp_f32_e32 v65, v65
	v_exp_f32_e32 v66, v66
	v_exp_f32_e32 v67, v67
	v_add_f32_e32 v64, 1.0, v64
	v_add_f32_e32 v65, 1.0, v65
	v_add_f32_e32 v66, 1.0, v66
	v_add_f32_e32 v67, 1.0, v67
	v_rcp_f32_e32 v64, v64
	v_rcp_f32_e32 v65, v65
	v_rcp_f32_e32 v66, v66
	v_rcp_f32_e32 v67, v67
	v_pk_mul_f32 v[60:61], v[60:61], v[64:65]
	v_mul_f32_e32 v64, 0xbfb8aa3b, v56
	v_mul_f32_e32 v65, 0xbfb8aa3b, v57
	v_pk_mul_f32 v[62:63], v[62:63], v[66:67]
	v_mul_f32_e32 v66, 0xbfb8aa3b, v58
	v_mul_f32_e32 v67, 0xbfb8aa3b, v59
	v_exp_f32_e32 v64, v64
	v_exp_f32_e32 v65, v65
	v_exp_f32_e32 v66, v66
	v_exp_f32_e32 v67, v67
	v_add_f32_e32 v64, 1.0, v64
	v_add_f32_e32 v65, 1.0, v65
	v_add_f32_e32 v66, 1.0, v66
	v_add_f32_e32 v67, 1.0, v67
	v_rcp_f32_e32 v64, v64
	v_rcp_f32_e32 v65, v65
	v_rcp_f32_e32 v66, v66
	v_rcp_f32_e32 v67, v67
	v_pk_mul_f32 v[52:53], v[60:61], v[52:53]
	v_pk_mul_f32 v[56:57], v[56:57], v[64:65]
	v_pk_mul_f32 v[54:55], v[62:63], v[54:55]
	v_pk_mul_f32 v[58:59], v[58:59], v[66:67]
	s_nop 0
	v_pk_mul_f32 v[58:59], v[58:59], v[50:51]
; __device__ __forceinline__ u32x4 pack8(const f32x4 v0, const f32x4 v1) { u32x4 w; w.x = cvt_pk_bf16(v0[0], v0[1]); w.y = cvt_pk_bf16(v0[2], v0[3]); w.z = cvt_pk_bf16(v1[0], v1[1]); w.w = cvt_pk_bf16(v1[2], v1[3]); return w; }
; __device__ __forceinline__ f32x4 sig4(const f32x4 v) { return (f32x4){sigmoidf_(v[0]), sigmoidf_(v[1]), sigmoidf_(v[2]), sigmoidf_(v[3])}; }
;     __device__ __forceinline__ void operator()(const AccT& acc, const pg8::Unit& u, int wr, int wc, int fr, int fq) const {
;         const int row0 = u.pm * 256 + wr * 64 + fr, col0 = u.pn * 128 + wc * 32 + 8 * fq;
; #pragma unroll
;         for (int ai = 0; ai < 2; ++ai)
; #pragma unroll
;             for (int m = 0; m < 4; ++m) { const int r = row0 + ai * 128 + m * 16;
;                 const f32x4 g0 = acc[ai][0][m][0], g1 = acc[ai][0][m][1];
;                 const f32x4 o0 = g0 * sig4(g0) * acc[ai][1][m][0], o1 = g1 * sig4(g1) * acc[ai][1][m][1];
;                 *(u32x4*)(O + (size_t)r * DFF + col0) = pack8(o0, o1); }
	v_pk_mul_f32 v[50:51], v[56:57], v[48:49]
	v_cvt_pk_bf16_f32 v48, v52, v53
	v_mad_i64_i32 v[52:53], s[22:23], v68, s42, v[112:113]
	v_cvt_pk_bf16_f32 v49, v54, v55
	v_cvt_pk_bf16_f32 v50, v50, v51
	v_cvt_pk_bf16_f32 v51, v58, v59
	v_lshl_add_u64 v[52:53], v[52:53], 0, v[114:115]
	global_store_dwordx4 v[52:53], v[48:51], off sc1
	v_add_u32_e32 v52, 0x90, v154
	s_nop 0
	v_mul_f32_e32 v48, 0xbfb8aa3b, v44
	v_mul_f32_e32 v49, 0xbfb8aa3b, v45
	v_mul_f32_e32 v50, 0xbfb8aa3b, v46
	v_mul_f32_e32 v51, 0xbfb8aa3b, v47
	v_exp_f32_e32 v48, v48
	v_exp_f32_e32 v49, v49
	v_exp_f32_e32 v50, v50
	v_exp_f32_e32 v51, v51
	v_add_f32_e32 v48, 1.0, v48
	v_add_f32_e32 v49, 1.0, v49
	v_add_f32_e32 v50, 1.0, v50
	v_add_f32_e32 v51, 1.0, v51
	v_rcp_f32_e32 v48, v48
	v_rcp_f32_e32 v49, v49
	v_rcp_f32_e32 v50, v50
	v_rcp_f32_e32 v51, v51
	v_pk_mul_f32 v[44:45], v[44:45], v[48:49]
	v_mul_f32_e32 v48, 0xbfb8aa3b, v40
	v_mul_f32_e32 v49, 0xbfb8aa3b, v41
	v_pk_mul_f32 v[46:47], v[46:47], v[50:51]
	v_mul_f32_e32 v50, 0xbfb8aa3b, v42
	v_mul_f32_e32 v51, 0xbfb8aa3b, v43
	v_exp_f32_e32 v48, v48
	v_exp_f32_e32 v49, v49
	v_exp_f32_e32 v50, v50
	v_exp_f32_e32 v51, v51
	v_add_f32_e32 v48, 1.0, v48
	v_add_f32_e32 v49, 1.0, v49
	v_add_f32_e32 v50, 1.0, v50
	v_add_f32_e32 v51, 1.0, v51
	v_rcp_f32_e32 v48, v48
	v_rcp_f32_e32 v49, v49
	v_rcp_f32_e32 v50, v50
	v_rcp_f32_e32 v51, v51
	v_pk_mul_f32 v[36:37], v[44:45], v[36:37]
	v_pk_mul_f32 v[40:41], v[40:41], v[48:49]
	v_pk_mul_f32 v[38:39], v[46:47], v[38:39]
	v_pk_mul_f32 v[42:43], v[42:43], v[50:51]
	s_nop 0
	v_pk_mul_f32 v[42:43], v[42:43], v[34:35]
	v_pk_mul_f32 v[34:35], v[40:41], v[32:33]
	v_cvt_pk_bf16_f32 v32, v36, v37
	v_mad_i64_i32 v[36:37], s[22:23], v52, s42, v[112:113]
	v_cvt_pk_bf16_f32 v33, v38, v39
	v_cvt_pk_bf16_f32 v34, v34, v35
	v_cvt_pk_bf16_f32 v35, v42, v43
	v_lshl_add_u64 v[36:37], v[36:37], 0, v[114:115]
	global_store_dwordx4 v[36:37], v[32:35], off sc1
	v_add_u32_e32 v36, 0xa0, v154
	s_nop 0
	v_mul_f32_e32 v32, 0xbfb8aa3b, v28
	v_mul_f32_e32 v33, 0xbfb8aa3b, v29
	v_mul_f32_e32 v34, 0xbfb8aa3b, v30
	v_mul_f32_e32 v35, 0xbfb8aa3b, v31
	v_exp_f32_e32 v32, v32
	v_exp_f32_e32 v33, v33
	v_exp_f32_e32 v34, v34
	v_exp_f32_e32 v35, v35
	v_add_f32_e32 v32, 1.0, v32
	v_add_f32_e32 v33, 1.0, v33
	v_add_f32_e32 v34, 1.0, v34
	v_add_f32_e32 v35, 1.0, v35
	v_rcp_f32_e32 v32, v32
	v_rcp_f32_e32 v33, v33
	v_rcp_f32_e32 v34, v34
	v_rcp_f32_e32 v35, v35
	v_pk_mul_f32 v[28:29], v[28:29], v[32:33]
	v_mul_f32_e32 v32, 0xbfb8aa3b, v24
	v_mul_f32_e32 v33, 0xbfb8aa3b, v25
	v_pk_mul_f32 v[30:31], v[30:31], v[34:35]
	v_mul_f32_e32 v34, 0xbfb8aa3b, v26
	v_mul_f32_e32 v35, 0xbfb8aa3b, v27
	v_exp_f32_e32 v32, v32
	v_exp_f32_e32 v33, v33
	v_exp_f32_e32 v34, v34
	v_exp_f32_e32 v35, v35
	v_add_f32_e32 v32, 1.0, v32
	v_add_f32_e32 v33, 1.0, v33
	v_add_f32_e32 v34, 1.0, v34
	v_add_f32_e32 v35, 1.0, v35
	v_rcp_f32_e32 v32, v32
	v_rcp_f32_e32 v33, v33
	v_rcp_f32_e32 v34, v34
	v_rcp_f32_e32 v35, v35
	v_pk_mul_f32 v[20:21], v[28:29], v[20:21]
	v_pk_mul_f32 v[24:25], v[24:25], v[32:33]
	v_pk_mul_f32 v[22:23], v[30:31], v[22:23]
	v_pk_mul_f32 v[26:27], v[26:27], v[34:35]
	s_nop 0
	v_pk_mul_f32 v[26:27], v[26:27], v[18:19]
	v_pk_mul_f32 v[18:19], v[24:25], v[16:17]
	v_cvt_pk_bf16_f32 v16, v20, v21
	v_mad_i64_i32 v[20:21], s[22:23], v36, s42, v[112:113]
	v_cvt_pk_bf16_f32 v17, v22, v23
	v_cvt_pk_bf16_f32 v18, v18, v19
	v_cvt_pk_bf16_f32 v19, v26, v27
	v_lshl_add_u64 v[20:21], v[20:21], 0, v[114:115]
	global_store_dwordx4 v[20:21], v[16:19], off sc1
	v_add_u32_e32 v20, 0xb0, v154
	s_nop 0
	v_mul_f32_e32 v16, 0xbfb8aa3b, v12
	v_mul_f32_e32 v17, 0xbfb8aa3b, v13
	v_mul_f32_e32 v18, 0xbfb8aa3b, v14
	v_mul_f32_e32 v19, 0xbfb8aa3b, v15
	v_exp_f32_e32 v16, v16
	v_exp_f32_e32 v17, v17
	v_exp_f32_e32 v18, v18
	v_exp_f32_e32 v19, v19
	v_add_f32_e32 v16, 1.0, v16
	v_add_f32_e32 v17, 1.0, v17
	v_add_f32_e32 v18, 1.0, v18
	v_add_f32_e32 v19, 1.0, v19
	v_rcp_f32_e32 v16, v16
	v_rcp_f32_e32 v17, v17
	v_rcp_f32_e32 v18, v18
	v_rcp_f32_e32 v19, v19
	v_pk_mul_f32 v[12:13], v[12:13], v[16:17]
	v_mul_f32_e32 v16, 0xbfb8aa3b, v8
	v_mul_f32_e32 v17, 0xbfb8aa3b, v9
	v_pk_mul_f32 v[14:15], v[14:15], v[18:19]
	v_mul_f32_e32 v18, 0xbfb8aa3b, v10
	v_mul_f32_e32 v19, 0xbfb8aa3b, v11
	v_exp_f32_e32 v16, v16
	v_exp_f32_e32 v17, v17
	v_exp_f32_e32 v18, v18
	v_exp_f32_e32 v19, v19
	v_add_f32_e32 v16, 1.0, v16
	v_add_f32_e32 v17, 1.0, v17
	v_add_f32_e32 v18, 1.0, v18
	v_add_f32_e32 v19, 1.0, v19
	v_rcp_f32_e32 v16, v16
	v_rcp_f32_e32 v17, v17
	v_rcp_f32_e32 v18, v18
	v_rcp_f32_e32 v19, v19
	v_pk_mul_f32 v[4:5], v[12:13], v[4:5]
	v_pk_mul_f32 v[8:9], v[8:9], v[16:17]
	v_pk_mul_f32 v[6:7], v[14:15], v[6:7]
	v_pk_mul_f32 v[10:11], v[10:11], v[18:19]
	s_nop 0
	v_pk_mul_f32 v[10:11], v[10:11], v[2:3]
	v_pk_mul_f32 v[2:3], v[8:9], v[0:1]
	v_cvt_pk_bf16_f32 v0, v4, v5
	v_mad_i64_i32 v[4:5], s[22:23], v20, s42, v[112:113]
	v_lshl_add_u64 v[4:5], v[4:5], 0, v[114:115]
	s_mov_b64 s[22:23], s[16:17]
	v_cvt_pk_bf16_f32 v1, v6, v7
	v_cvt_pk_bf16_f32 v2, v2, v3
	v_cvt_pk_bf16_f32 v3, v10, v11
	global_store_dwordx4 v[4:5], v[0:3], off sc1
	s_cbranch_vccz .LBB0_1143
	s_waitcnt vmcnt(0)
	s_cmpk_gt_u32 s28, 0xff
	s_cbranch_scc1 .LBB0_1154
	s_barrier

; __device__ __forceinline__ unsigned cvt_pk_bf16(float lo, float hi) { unsigned r; asm volatile("v_cvt_pk_bf16_f32 %0, %1, %2" : "=v"(r) : "v"(lo), "v"(hi)); return r; }
; __device__ __forceinline__ void convert_dynamic(const Params& P, unsigned char* shm, unsigned* ctr, int t0, int t1) {
;     ...
;         for (int h = 0; h < 4; ++h) { d[h] = tile_desc(P, t + h < t1 ? t + h : t);
; #pragma unroll
;             for (int i = 0; i < 4; ++i) v[h][i] = *(const f32x4*)(d[h].src + (size_t)(r0 + 32 * i) * d[h].ld + c4 * 4); }
; #pragma unroll
;         for (int h = 0; h < 4; ++h) {
;             if (t + h < t1) {
; #pragma unroll
;                 for (int i = 0; i < 4; ++i) { float* tp = tile + (r0 + 32 * i) * 65 + c4 * 4; tp[0] = v[h][i][0]; tp[1] = v[h][i][1]; tp[2] = v[h][i][2]; tp[3] = v[h][i][3]; }
;                 __syncthreads();
;                 { const int n = tid >> 3, kc = tid & 7; float x[16];
; #pragma unroll
;                   for (int jj = 0; jj < 8; ++jj) { x[jj] = tile[(kc * 8 + jj) * 65 + n]; x[8 + jj] = tile[(64 + kc * 8 + jj) * 65 + n]; }
;                   u32x4 w0, w1; w0.x = cvt_pk_bf16(x[0], x[1]); w0.y = cvt_pk_bf16(x[2], x[3]); w0.z = cvt_pk_bf16(x[4], x[5]); w0.w = cvt_pk_bf16(x[6], x[7]);
;                   w1.x = cvt_pk_bf16(x[8], x[9]); w1.y = cvt_pk_bf16(x[10], x[11]); w1.z = cvt_pk_bf16(x[12], x[13]); w1.w = cvt_pk_bf16(x[14], x[15]);
;                   bf16_t* dp = d[h].dst + (size_t)n * d[h].ldd + kc * 8; *(u32x4*)dp = w0; *(u32x4*)(dp + 64) = w1; }
;                 __syncthreads();
.LBB0_1259:
	s_or_b64 exec, exec, s[34:35]
	v_lshl_add_u64 v[58:59], v[48:49], 0, v[66:67]
	v_mul_u32_u24_e32 v48, v56, v145
	v_lshlrev_b32_e32 v66, 2, v48
	v_mul_hi_u32_u24_e32 v51, v56, v65
	v_mul_u32_u24_e32 v50, v56, v65
	v_mul_hi_u32_u24_e32 v61, v56, v69
	v_mul_u32_u24_e32 v60, v56, v69
	v_mul_hi_u32_u24_e32 v57, v56, v86
	v_mul_u32_u24_e32 v56, v56, v86
	v_lshl_add_u64 v[48:49], v[58:59], 0, v[66:67]
	v_lshl_add_u64 v[50:51], v[50:51], 2, v[58:59]
	v_lshl_add_u64 v[60:61], v[60:61], 2, v[58:59]
	v_lshl_add_u64 v[56:57], v[56:57], 2, v[58:59]
	global_load_dwordx4 v[52:55], v[48:49], off
	s_nop 0
	global_load_dwordx4 v[48:51], v[50:51], off
	s_nop 0
	global_load_dwordx4 v[60:63], v[60:61], off
	s_nop 0
	global_load_dwordx4 v[56:59], v[56:57], off
	s_waitcnt vmcnt(15)
	ds_write2_b32 v90, v4, v5 offset1:1
	ds_write2_b32 v90, v6, v7 offset0:2 offset1:3
	v_add_u32_e32 v4, 0x2080, v90
	s_waitcnt vmcnt(14)
	ds_write2_b32 v4, v0, v1 offset1:1
	v_add_u32_e32 v0, 0x2088, v90
	ds_write2_b32 v0, v2, v3 offset1:1
	v_add_u32_e32 v1, 0x4100, v90
	v_add_u32_e32 v2, 0x4108, v90
	v_add_u32_e32 v5, 0x6180, v90
	v_add_u32_e32 v6, 0x6188, v90
	v_add_u32_e32 v3, 0x400, v87
	s_waitcnt vmcnt(13)
	ds_write2_b32 v1, v12, v13 offset1:1
	ds_write2_b32 v2, v14, v15 offset1:1
	s_waitcnt vmcnt(12)
	ds_write2_b32 v5, v8, v9 offset1:1
	ds_write2_b32 v6, v10, v11 offset1:1
	s_waitcnt lgkmcnt(0)
	s_barrier
	ds_read2_b32 v[12:13], v87 offset1:65
	ds_read2_b32 v[14:15], v87 offset0:130 offset1:195
	ds_read2_b32 v[92:93], v3 offset0:4 offset1:69
	ds_read2_b32 v[94:95], v3 offset0:134 offset1:199
	v_mul_u32_u24_e32 v11, v72, v144
	v_lshlrev_b32_e32 v66, 1, v11
	v_add_u32_e32 v7, 0x4000, v88
	v_add_u32_e32 v8, 0x4200, v88
	v_add_u32_e32 v9, 0x4400, v88
	v_add_u32_e32 v10, 0x4600, v88
	v_lshl_add_u64 v[70:71], v[70:71], 0, v[66:67]
	v_lshlrev_b32_e32 v66, 1, v68
	ds_read2_b32 v[96:97], v7 offset0:64 offset1:129
	ds_read2_b32 v[98:99], v8 offset0:66 offset1:131
	ds_read2_b32 v[100:101], v9 offset0:68 offset1:133
	ds_read2_b32 v[102:103], v10 offset0:70 offset1:135
	s_waitcnt lgkmcnt(7)
	v_cvt_pk_bf16_f32 v12, v12, v13
	s_waitcnt lgkmcnt(6)
	v_cvt_pk_bf16_f32 v13, v14, v15
	s_waitcnt lgkmcnt(5)
	v_cvt_pk_bf16_f32 v14, v92, v93
	s_waitcnt lgkmcnt(4)
	v_cvt_pk_bf16_f32 v15, v94, v95
	v_lshl_add_u64 v[70:71], v[70:71], 0, v[66:67]
	s_waitcnt lgkmcnt(3)
	v_cvt_pk_bf16_f32 v92, v96, v97
	s_waitcnt lgkmcnt(2)
	v_cvt_pk_bf16_f32 v93, v98, v99
	s_waitcnt lgkmcnt(1)
	v_cvt_pk_bf16_f32 v94, v100, v101
	s_waitcnt lgkmcnt(0)
	v_cvt_pk_bf16_f32 v95, v102, v103
	global_store_dwordx4 v[70:71], v[12:15], off sc1
	global_store_dwordx4 v[70:71], v[92:95], off offset:128 sc1
	s_barrier
	s_and_saveexec_b64 s[0:1], vcc
	s_cbranch_execnz .LBB0_1262
	s_or_b64 exec, exec, s[0:1]
	s_and_saveexec_b64 s[0:1], s[2:3]
	s_cbranch_execnz .LBB0_1263

; __device__ __forceinline__ unsigned cvt_pk_bf16(float lo, float hi) { unsigned r; asm volatile("v_cvt_pk_bf16_f32 %0, %1, %2" : "=v"(r) : "v"(lo), "v"(hi)); return r; }
; __device__ __forceinline__ void convert_dynamic(const Params& P, unsigned char* shm, unsigned* ctr, int t0, int t1) {
;     ...
;         for (int h = 0; h < 4; ++h) {
;             if (t + h < t1) {
; #pragma unroll
;                 for (int i = 0; i < 4; ++i) { float* tp = tile + (r0 + 32 * i) * 65 + c4 * 4; tp[0] = v[h][i][0]; tp[1] = v[h][i][1]; tp[2] = v[h][i][2]; tp[3] = v[h][i][3]; }
;                 __syncthreads();
;                 { const int n = tid >> 3, kc = tid & 7; float x[16];
; #pragma unroll
;                   for (int jj = 0; jj < 8; ++jj) { x[jj] = tile[(kc * 8 + jj) * 65 + n]; x[8 + jj] = tile[(64 + kc * 8 + jj) * 65 + n]; }
;                   u32x4 w0, w1; w0.x = cvt_pk_bf16(x[0], x[1]); w0.y = cvt_pk_bf16(x[2], x[3]); w0.z = cvt_pk_bf16(x[4], x[5]); w0.w = cvt_pk_bf16(x[6], x[7]);
;                   w1.x = cvt_pk_bf16(x[8], x[9]); w1.y = cvt_pk_bf16(x[10], x[11]); w1.z = cvt_pk_bf16(x[12], x[13]); w1.w = cvt_pk_bf16(x[14], x[15]);
;                   bf16_t* dp = d[h].dst + (size_t)n * d[h].ldd + kc * 8; *(u32x4*)dp = w0; *(u32x4*)(dp + 64) = w1; }
;                 __syncthreads();
.LBB0_1262:
	s_waitcnt vmcnt(13)
	ds_write2_b32 v90, v20, v21 offset1:1
	ds_write2_b32 v90, v22, v23 offset0:2 offset1:3
	s_waitcnt vmcnt(12)
	ds_write2_b32 v4, v16, v17 offset1:1
	ds_write2_b32 v0, v18, v19 offset1:1
	s_waitcnt vmcnt(11)
	ds_write2_b32 v1, v28, v29 offset1:1
	ds_write2_b32 v2, v30, v31 offset1:1
	s_waitcnt vmcnt(10)
	ds_write2_b32 v5, v24, v25 offset1:1
	ds_write2_b32 v6, v26, v27 offset1:1
	s_waitcnt lgkmcnt(0)
	s_barrier
	ds_read2_b32 v[12:13], v87 offset1:65
	ds_read2_b32 v[14:15], v87 offset0:130 offset1:195
	ds_read2_b32 v[16:17], v3 offset0:4 offset1:69
	ds_read2_b32 v[18:19], v3 offset0:134 offset1:199
	ds_read2_b32 v[20:21], v7 offset0:64 offset1:129
	ds_read2_b32 v[22:23], v8 offset0:66 offset1:131
	ds_read2_b32 v[24:25], v9 offset0:68 offset1:133
	ds_read2_b32 v[26:27], v10 offset0:70 offset1:135
	v_mul_u32_u24_e32 v11, v76, v144
	s_waitcnt lgkmcnt(7)
	v_cvt_pk_bf16_f32 v12, v12, v13
	s_waitcnt lgkmcnt(6)
	v_cvt_pk_bf16_f32 v13, v14, v15
	s_waitcnt lgkmcnt(5)
	v_cvt_pk_bf16_f32 v14, v16, v17
	s_waitcnt lgkmcnt(4)
	v_cvt_pk_bf16_f32 v15, v18, v19
	s_waitcnt lgkmcnt(3)
	v_cvt_pk_bf16_f32 v16, v20, v21
	v_lshlrev_b32_e32 v20, 1, v11
	v_mov_b32_e32 v21, v67
	v_lshl_add_u64 v[20:21], v[74:75], 0, v[20:21]
	v_lshl_add_u64 v[20:21], v[20:21], 0, v[66:67]
	s_waitcnt lgkmcnt(2)
	v_cvt_pk_bf16_f32 v17, v22, v23
	s_waitcnt lgkmcnt(1)
	v_cvt_pk_bf16_f32 v18, v24, v25
	s_waitcnt lgkmcnt(0)
	v_cvt_pk_bf16_f32 v19, v26, v27
	global_store_dwordx4 v[20:21], v[12:15], off sc1
	global_store_dwordx4 v[20:21], v[16:19], off offset:128 sc1
	s_barrier
	s_or_b64 exec, exec, s[0:1]
	s_and_saveexec_b64 s[0:1], s[2:3]
	s_cbranch_execz .LBB0_1261
.LBB0_1263:
	s_waitcnt vmcnt(9)
	ds_write2_b32 v90, v36, v37 offset1:1
	ds_write2_b32 v90, v38, v39 offset0:2 offset1:3
	s_waitcnt vmcnt(8)
	ds_write2_b32 v4, v32, v33 offset1:1
	ds_write2_b32 v0, v34, v35 offset1:1
	s_waitcnt vmcnt(7)
	ds_write2_b32 v1, v44, v45 offset1:1
	ds_write2_b32 v2, v46, v47 offset1:1
	s_waitcnt vmcnt(6)
	ds_write2_b32 v5, v40, v41 offset1:1
	ds_write2_b32 v6, v42, v43 offset1:1
	s_waitcnt lgkmcnt(0)
	s_barrier
	ds_read2_b32 v[12:13], v87 offset1:65
	ds_read2_b32 v[14:15], v87 offset0:130 offset1:195
	ds_read2_b32 v[16:17], v3 offset0:4 offset1:69
	ds_read2_b32 v[18:19], v3 offset0:134 offset1:199
	ds_read2_b32 v[20:21], v7 offset0:64 offset1:129
	ds_read2_b32 v[22:23], v8 offset0:66 offset1:131
	ds_read2_b32 v[24:25], v9 offset0:68 offset1:133
	ds_read2_b32 v[26:27], v10 offset0:70 offset1:135
	v_mul_u32_u24_e32 v11, v80, v144
	s_waitcnt lgkmcnt(7)
	v_cvt_pk_bf16_f32 v12, v12, v13
	s_waitcnt lgkmcnt(6)
	v_cvt_pk_bf16_f32 v13, v14, v15
	s_waitcnt lgkmcnt(5)
	v_cvt_pk_bf16_f32 v14, v16, v17
	s_waitcnt lgkmcnt(4)
	v_cvt_pk_bf16_f32 v15, v18, v19
	s_waitcnt lgkmcnt(3)
	v_cvt_pk_bf16_f32 v16, v20, v21
	v_lshlrev_b32_e32 v20, 1, v11
	v_mov_b32_e32 v21, v67
	v_lshl_add_u64 v[20:21], v[78:79], 0, v[20:21]
	v_lshl_add_u64 v[20:21], v[20:21], 0, v[66:67]
	s_waitcnt lgkmcnt(2)
	v_cvt_pk_bf16_f32 v17, v22, v23
	s_waitcnt lgkmcnt(1)
	v_cvt_pk_bf16_f32 v18, v24, v25
	s_waitcnt lgkmcnt(0)
	v_cvt_pk_bf16_f32 v19, v26, v27
	global_store_dwordx4 v[20:21], v[12:15], off sc1
	global_store_dwordx4 v[20:21], v[16:19], off offset:128 sc1
	s_barrier
	s_or_b64 exec, exec, s[0:1]
	s_and_saveexec_b64 s[0:1], s[4:5]
	s_xor_b64 s[0:1], exec, s[0:1]
	s_cbranch_execz .LBB0_1156
.LBB0_1264:
	s_waitcnt vmcnt(5)
	ds_write2_b32 v90, v52, v53 offset1:1
	ds_write2_b32 v90, v54, v55 offset0:2 offset1:3
	s_waitcnt vmcnt(4)
	ds_write2_b32 v4, v48, v49 offset1:1
	ds_write2_b32 v0, v50, v51 offset1:1
	s_waitcnt vmcnt(3)
	ds_write2_b32 v1, v60, v61 offset1:1
	ds_write2_b32 v2, v62, v63 offset1:1
	s_waitcnt vmcnt(2)
	ds_write2_b32 v5, v56, v57 offset1:1
	ds_write2_b32 v6, v58, v59 offset1:1
	s_waitcnt lgkmcnt(0)
	s_barrier
	ds_read2_b32 v[0:1], v87 offset1:65
	ds_read2_b32 v[4:5], v87 offset0:130 offset1:195
	ds_read2_b32 v[12:13], v3 offset0:4 offset1:69
	ds_read2_b32 v[14:15], v3 offset0:134 offset1:199
	ds_read2_b32 v[6:7], v7 offset0:64 offset1:129
	ds_read2_b32 v[16:17], v8 offset0:66 offset1:131
	ds_read2_b32 v[8:9], v9 offset0:68 offset1:133
	ds_read2_b32 v[10:11], v10 offset0:70 offset1:135
	s_waitcnt lgkmcnt(7)
	v_cvt_pk_bf16_f32 v0, v0, v1
	s_waitcnt lgkmcnt(6)
	v_cvt_pk_bf16_f32 v1, v4, v5
	s_waitcnt lgkmcnt(5)
	v_cvt_pk_bf16_f32 v2, v12, v13
	s_waitcnt lgkmcnt(4)
	v_cvt_pk_bf16_f32 v3, v14, v15
	s_waitcnt lgkmcnt(3)
	v_cvt_pk_bf16_f32 v4, v6, v7
	s_waitcnt lgkmcnt(2)
	v_cvt_pk_bf16_f32 v5, v16, v17
	s_waitcnt lgkmcnt(1)
	v_cvt_pk_bf16_f32 v6, v8, v9
	v_mul_u32_u24_e32 v8, v84, v144
	v_lshlrev_b32_e32 v8, 1, v8
	v_mov_b32_e32 v9, v67
	v_lshl_add_u64 v[8:9], v[82:83], 0, v[8:9]
	v_lshl_add_u64 v[8:9], v[8:9], 0, v[66:67]
	s_waitcnt lgkmcnt(0)
	v_cvt_pk_bf16_f32 v7, v10, v11
	global_store_dwordx4 v[8:9], v[0:3], off sc1
	global_store_dwordx4 v[8:9], v[4:7], off offset:128 sc1
	s_barrier
	s_branch .LBB0_1156
